# weight-copy prefetch depth 1 instead of 2 (gentler on the late-tile workgroups' memory traffic)
# speedup vs baseline: 1.0023x; 1.0008x over previous
; #define GAS __attribute__((address_space(1)))
; __device__ __forceinline__ void p0_transpose_item(const float* W, int ldw, int src_col0, int k0, bf16_t* WT, int ldk, int dst_row0, int dst_k0, LAS float* scr, int lane) {
; #pragma unroll
;     for (int i = 0; i < 8; ++i) { const int kk = 8 * i + (lane >> 3), n4 = 4 * (lane & 7);
;         const f32x4 w = *(const GAS f32x4*)(W + (size_t)(k0 + kk) * ldw + src_col0 + n4); LAS float* d = scr + kk * 33 + n4; d[0] = w[0]; d[1] = w[1]; d[2] = w[2]; d[3] = w[3]; }
;     LDS_WAIT(); asm volatile("" ::: "memory");
;     const int c = lane & 7;
; #pragma unroll
;     for (int j = 0; j < 4; ++j) { const int n = (lane >> 3) + 8 * j; const LAS float* s = scr + (8 * c) * 33 + n;
;         v4u o; o.x = pk2(s[0 * 33], s[1 * 33]); o.y = pk2(s[2 * 33], s[3 * 33]); o.z = pk2(s[4 * 33], s[5 * 33]); o.w = pk2(s[6 * 33], s[7 * 33]);
;         *(GAS v4u*)(WT + (size_t)(dst_row0 + n) * ldk + dst_k0 + k0 + 8 * c) = o; }
;     LDS_WAIT(); asm volatile("" ::: "memory");
; __global__ void __launch_bounds__(NWAVES * 64, 2) fwd(Args args) {
;     ...
;             {
;                 __syncthreads();
;                 LAS float* scr = (LAS float*)(lds + RING_OFF + wave * 8704);
;                 constexpr int I_BA = 8 * 32, I_BB = 8 * 32, I_O = 16 * 32, I_UP = 16 * 128, I_DN = 64 * 32;
;                 if (blockIdx.x < 64) for (int it = ((int)blockIdx.x - 32) * NWAVES + wave; it < I_BA + I_BB + I_O + I_UP + I_DN; it += 32 * NWAVES) {
;                     int r = it;
;                     if (r < I_BA) { const int kb = r / 32, nb = r % 32; p0_transpose_item(wba, 1024, 32 * nb, 64 * kb, WBAB_T, 1024, 32 * nb, 0, scr, lane); continue; } r -= I_BA;
;                     if (r < I_BB) { const int kb = r / 32, nb = r % 32; p0_transpose_item(wbb, 1024, 32 * nb, 64 * kb, WBAB_T, 1024, 32 * nb, 512, scr, lane); continue; } r -= I_BB;
;                     if (r < I_O) { const int kb = r / 32, nb = r % 32; p0_transpose_item(wo, 1024, 32 * nb, 64 * kb, WO_T, 1024, 32 * nb, 0, scr, lane); continue; } r -= I_O;
;                     if (r < I_UP) { const int kb = r / 128, nb = r % 128; p0_transpose_item(wup, FF, 32 * nb, 64 * kb, WUP_T, 1024, 32 * nb, 0, scr, lane); continue; } r -= I_UP;
;                     { const int kb = r / 32, nb = r % 32; p0_transpose_item(wdn, 1024, 32 * nb, 64 * kb, WDN_T, FF, 32 * nb, 0, scr, lane); }
;                 }
.LBB0_818:
	s_andn2_b64 vcc, exec, s[38:39]
	s_waitcnt vmcnt(0)
	s_barrier
	s_cbranch_vccnz .LBB0_839
	s_add_i32 s0, s72, s48
	s_add_i32 s4, s0, 0xffffff00
	s_cmp_lt_i32 s4, 0
	s_cbranch_scc1 .LBB0_839
	s_cmpk_gt_i32 s4, 0xff
	s_cbranch_scc1 .LBB0_839
	v_readlane_b32 s68, v240, 8
	v_readlane_b32 s69, v240, 9
	v_readlane_b32 s70, v240, 10
	v_readlane_b32 s71, v240, 11
	v_readlane_b32 s74, v240, 12
	v_readlane_b32 s75, v240, 13
	v_readlane_b32 s78, v240, 18
	v_readlane_b32 s79, v240, 19
	v_readlane_b32 s80, v240, 20
	v_readlane_b32 s81, v240, 21
	v_and_b32_e32 v2, 7, v234
	v_lshrrev_b32_e32 v1, 3, v234
	v_lshlrev_b32_e32 v3, 4, v2
	s_mul_i32 s0, s48, 0x2200
	v_mul_u32_u24_e32 v4, 0x84, v1
	v_add3_u32 v32, s0, v3, v4
	v_add_u32_e32 v33, 0x420, v32
	v_add_u32_e32 v34, 0x428, v32
	v_add_u32_e32 v35, 0x840, v32
	v_add_u32_e32 v36, 0x848, v32
	v_add_u32_e32 v37, 0xc60, v32
	v_add_u32_e32 v38, 0xc68, v32
	v_add_u32_e32 v39, 0x1080, v32
	v_add_u32_e32 v40, 0x1088, v32
	v_add_u32_e32 v41, 0x14a0, v32
	v_add_u32_e32 v42, 0x14a8, v32
	v_add_u32_e32 v43, 0x18c0, v32
	v_add_u32_e32 v44, 0x18c8, v32
	v_add_u32_e32 v45, 0x1ce0, v32
	v_add_u32_e32 v46, 0x1ce8, v32
	v_lshlrev_b32_e32 v5, 3, v2
	v_mul_u32_u24_e32 v5, 0x84, v5
	v_lshlrev_b32_e32 v6, 2, v1
	v_add3_u32 v31, s0, v5, v6
	v_lshl_or_b32 v100, v1, 12, v3
	v_add_u32_e32 v101, 0x8000, v100
	v_add_u32_e32 v102, 0x10000, v100
	v_add_u32_e32 v103, 0x18000, v100
	v_add_u32_e32 v104, 0x20000, v100
	v_add_u32_e32 v105, 0x28000, v100
	v_add_u32_e32 v106, 0x30000, v100
	v_add_u32_e32 v107, 0x38000, v100
	v_lshl_or_b32 v108, v1, 14, v3
	v_add_u32_e32 v109, 0x20000, v108
	v_add_u32_e32 v110, 0x40000, v108
	v_add_u32_e32 v111, 0x60000, v108
	v_add_u32_e32 v112, 0x80000, v108
	v_add_u32_e32 v113, 0xa0000, v108
	v_add_u32_e32 v114, 0xc0000, v108
	v_add_u32_e32 v115, 0xe0000, v108
	v_lshl_or_b32 v116, v1, 11, v3
	v_add_u32_e32 v117, 0x4000, v116
	v_add_u32_e32 v118, 0x8000, v116
	v_add_u32_e32 v119, 0xc000, v116
	v_lshl_or_b32 v120, v1, 13, v3
	v_add_u32_e32 v121, 0x10000, v120
	v_add_u32_e32 v122, 0x20000, v120
	v_add_u32_e32 v123, 0x30000, v120
	s_lshr_b32 s5, s4, 5
	s_and_b32 s6, s4, 31
	s_lshr_b32 s7, s4, 7
	s_and_b32 s8, s4, 0x7f
	s_lshl_b32 s9, s5, 18
	s_lshl_b32 s10, s6, 7
	s_add_u32 s9, s9, s10
	s_lshl_b32 s10, s7, 20
	s_lshl_b32 s11, s8, 7
	s_add_u32 s10, s10, s11
	s_add_u32 s40, s68, s9
	s_addc_u32 s41, s69, 0
	s_add_u32 s42, s70, s9
	s_addc_u32 s43, s71, 0
	s_add_u32 s44, s74, s9
	s_addc_u32 s45, s75, 0
	s_add_u32 s46, s78, s10
	s_addc_u32 s47, s79, 0
	s_add_u32 s50, s80, s9
	s_addc_u32 s51, s81, 0
	s_lshl_b32 s9, s6, 16
	s_lshl_b32 s11, s5, 7
	s_add_u32 s9, s9, s11
	s_lshl_b32 s10, s8, 16
	s_lshl_b32 s19, s7, 7
	s_add_u32 s10, s10, s19
	s_lshl_b32 s18, s6, 18
	s_add_u32 s18, s18, s11
	s_add_u32 s82, s22, s9
	s_addc_u32 s83, s23, 0
	s_add_u32 s84, s16, s9
	s_addc_u32 s85, s17, 0
	s_add_u32 s86, s14, s10
	s_addc_u32 s87, s15, 0
	s_add_u32 s88, s12, s18
	s_addc_u32 s89, s13, 0
	s_add_u32 s76, s88, 0x1000
	s_addc_u32 s77, s89, 0
	global_load_dwordx4 v[128:131], v100, s[40:41] nt
	global_load_dwordx4 v[132:135], v101, s[40:41] nt
	global_load_dwordx4 v[136:139], v102, s[40:41] nt
	global_load_dwordx4 v[140:143], v103, s[40:41] nt
	global_load_dwordx4 v[144:147], v104, s[40:41] nt
	global_load_dwordx4 v[148:151], v105, s[40:41] nt
	global_load_dwordx4 v[152:155], v106, s[40:41] nt
	global_load_dwordx4 v[156:159], v107, s[40:41] nt
	global_load_dwordx4 v[160:163], v100, s[42:43] nt
	global_load_dwordx4 v[164:167], v101, s[42:43] nt
	global_load_dwordx4 v[168:171], v102, s[42:43] nt
	global_load_dwordx4 v[172:175], v103, s[42:43] nt
	global_load_dwordx4 v[176:179], v104, s[42:43] nt
	global_load_dwordx4 v[180:183], v105, s[42:43] nt
	global_load_dwordx4 v[184:187], v106, s[42:43] nt
	global_load_dwordx4 v[188:191], v107, s[42:43] nt
	s_waitcnt vmcnt(8)
	ds_write2_b32 v32, v128, v129 offset1:1
	ds_write2_b32 v32, v130, v131 offset0:2 offset1:3
	ds_write2_b32 v33, v132, v133 offset1:1
	ds_write2_b32 v34, v134, v135 offset1:1
	ds_write2_b32 v35, v136, v137 offset1:1
	ds_write2_b32 v36, v138, v139 offset1:1
	ds_write2_b32 v37, v140, v141 offset1:1
	ds_write2_b32 v38, v142, v143 offset1:1
	ds_write2_b32 v39, v144, v145 offset1:1
	ds_write2_b32 v40, v146, v147 offset1:1
	ds_write2_b32 v41, v148, v149 offset1:1
	ds_write2_b32 v42, v150, v151 offset1:1
	ds_write2_b32 v43, v152, v153 offset1:1
	ds_write2_b32 v44, v154, v155 offset1:1
	ds_write2_b32 v45, v156, v157 offset1:1
	ds_write2_b32 v46, v158, v159 offset1:1
	s_waitcnt lgkmcnt(0)
	ds_read2_b32 v[48:49], v31 offset0:0 offset1:8
	ds_read2_b32 v[50:51], v31 offset0:33 offset1:41
	ds_read2_b32 v[52:53], v31 offset0:66 offset1:74
	ds_read2_b32 v[54:55], v31 offset0:99 offset1:107
	ds_read2_b32 v[56:57], v31 offset0:132 offset1:140
	ds_read2_b32 v[58:59], v31 offset0:165 offset1:173
	ds_read2_b32 v[60:61], v31 offset0:198 offset1:206
	ds_read2_b32 v[62:63], v31 offset0:231 offset1:239
	ds_read2_b32 v[64:65], v31 offset0:16 offset1:24
	ds_read2_b32 v[66:67], v31 offset0:49 offset1:57
	ds_read2_b32 v[68:69], v31 offset0:82 offset1:90
	ds_read2_b32 v[70:71], v31 offset0:115 offset1:123
	ds_read2_b32 v[72:73], v31 offset0:148 offset1:156
	ds_read2_b32 v[74:75], v31 offset0:181 offset1:189
	ds_read2_b32 v[76:77], v31 offset0:214 offset1:222
	ds_read2_b32 v[78:79], v31 offset0:247 offset1:255
	s_waitcnt lgkmcnt(8)
	v_cvt_pk_bf16_f32 v80, v48, v50
	v_cvt_pk_bf16_f32 v81, v52, v54
	v_cvt_pk_bf16_f32 v82, v56, v58
	v_cvt_pk_bf16_f32 v83, v60, v62
	v_cvt_pk_bf16_f32 v84, v49, v51
	v_cvt_pk_bf16_f32 v85, v53, v55
	v_cvt_pk_bf16_f32 v86, v57, v59
	v_cvt_pk_bf16_f32 v87, v61, v63
	s_waitcnt lgkmcnt(0)
; #define GAS __attribute__((address_space(1)))
; #define LAS __attribute__((address_space(3)))
; #define LDS_WAIT() asm volatile("s_waitcnt lgkmcnt(0)" ::: "memory")
; __device__ __forceinline__ unsigned pk2(float lo, float hi) { const f32x2_t v = {lo, hi}; return __builtin_bit_cast(unsigned, __builtin_convertvector(v, bf16x2_t)); }
; __device__ __forceinline__ void p0_transpose_item(const float* W, int ldw, int src_col0, int k0, bf16_t* WT, int ldk, int dst_row0, int dst_k0, LAS float* scr, int lane) {
; #pragma unroll
;     for (int i = 0; i < 8; ++i) { const int kk = 8 * i + (lane >> 3), n4 = 4 * (lane & 7);
;         const f32x4 w = *(const GAS f32x4*)(W + (size_t)(k0 + kk) * ldw + src_col0 + n4); LAS float* d = scr + kk * 33 + n4; d[0] = w[0]; d[1] = w[1]; d[2] = w[2]; d[3] = w[3]; }
;     LDS_WAIT(); asm volatile("" ::: "memory");
;     const int c = lane & 7;
; #pragma unroll
;     for (int j = 0; j < 4; ++j) { const int n = (lane >> 3) + 8 * j; const LAS float* s = scr + (8 * c) * 33 + n;
;         v4u o; o.x = pk2(s[0 * 33], s[1 * 33]); o.y = pk2(s[2 * 33], s[3 * 33]); o.z = pk2(s[4 * 33], s[5 * 33]); o.w = pk2(s[6 * 33], s[7 * 33]);
;         *(GAS v4u*)(WT + (size_t)(dst_row0 + n) * ldk + dst_k0 + k0 + 8 * c) = o; }
;     LDS_WAIT(); asm volatile("" ::: "memory");
; }
; __global__ void __launch_bounds__(NWAVES * 64, 2) fwd(Args args) {
;     ...
;                     if (r < I_BA) { const int kb = r / 32, nb = r % 32; p0_transpose_item(wba, 1024, 32 * nb, 64 * kb, WBAB_T, 1024, 32 * nb, 0, scr, lane); continue; } r -= I_BA;
;                     if (r < I_BB) { const int kb = r / 32, nb = r % 32; p0_transpose_item(wbb, 1024, 32 * nb, 64 * kb, WBAB_T, 1024, 32 * nb, 512, scr, lane); continue; } r -= I_BB;
;                     if (r < I_O) { const int kb = r / 32, nb = r % 32; p0_transpose_item(wo, 1024, 32 * nb, 64 * kb, WO_T, 1024, 32 * nb, 0, scr, lane); continue; } r -= I_O;
	v_cvt_pk_bf16_f32 v88, v64, v66
	v_cvt_pk_bf16_f32 v89, v68, v70
	v_cvt_pk_bf16_f32 v90, v72, v74
	v_cvt_pk_bf16_f32 v91, v76, v78
	v_cvt_pk_bf16_f32 v92, v65, v67
	v_cvt_pk_bf16_f32 v93, v69, v71
	v_cvt_pk_bf16_f32 v94, v73, v75
	v_cvt_pk_bf16_f32 v95, v77, v79
	global_store_dwordx4 v116, v[80:83], s[82:83]
	global_store_dwordx4 v117, v[84:87], s[82:83]
	global_store_dwordx4 v118, v[88:91], s[82:83]
	global_store_dwordx4 v119, v[92:95], s[82:83]
	global_load_dwordx4 v[128:131], v100, s[44:45] nt
	global_load_dwordx4 v[132:135], v101, s[44:45] nt
	global_load_dwordx4 v[136:139], v102, s[44:45] nt
	global_load_dwordx4 v[140:143], v103, s[44:45] nt
	global_load_dwordx4 v[144:147], v104, s[44:45] nt
	global_load_dwordx4 v[148:151], v105, s[44:45] nt
	global_load_dwordx4 v[152:155], v106, s[44:45] nt
	global_load_dwordx4 v[156:159], v107, s[44:45] nt
	s_waitcnt vmcnt(8)
	ds_write2_b32 v32, v160, v161 offset1:1
	ds_write2_b32 v32, v162, v163 offset0:2 offset1:3
	ds_write2_b32 v33, v164, v165 offset1:1
	ds_write2_b32 v34, v166, v167 offset1:1
	ds_write2_b32 v35, v168, v169 offset1:1
	ds_write2_b32 v36, v170, v171 offset1:1
	ds_write2_b32 v37, v172, v173 offset1:1
	ds_write2_b32 v38, v174, v175 offset1:1
	ds_write2_b32 v39, v176, v177 offset1:1
	ds_write2_b32 v40, v178, v179 offset1:1
	ds_write2_b32 v41, v180, v181 offset1:1
	ds_write2_b32 v42, v182, v183 offset1:1
	ds_write2_b32 v43, v184, v185 offset1:1
	ds_write2_b32 v44, v186, v187 offset1:1
	ds_write2_b32 v45, v188, v189 offset1:1
	ds_write2_b32 v46, v190, v191 offset1:1
	s_waitcnt lgkmcnt(0)
	ds_read2_b32 v[48:49], v31 offset0:0 offset1:8
	ds_read2_b32 v[50:51], v31 offset0:33 offset1:41
	ds_read2_b32 v[52:53], v31 offset0:66 offset1:74
	ds_read2_b32 v[54:55], v31 offset0:99 offset1:107
	ds_read2_b32 v[56:57], v31 offset0:132 offset1:140
	ds_read2_b32 v[58:59], v31 offset0:165 offset1:173
	ds_read2_b32 v[60:61], v31 offset0:198 offset1:206
	ds_read2_b32 v[62:63], v31 offset0:231 offset1:239
	ds_read2_b32 v[64:65], v31 offset0:16 offset1:24
	ds_read2_b32 v[66:67], v31 offset0:49 offset1:57
	ds_read2_b32 v[68:69], v31 offset0:82 offset1:90
	ds_read2_b32 v[70:71], v31 offset0:115 offset1:123
	ds_read2_b32 v[72:73], v31 offset0:148 offset1:156
	ds_read2_b32 v[74:75], v31 offset0:181 offset1:189
	ds_read2_b32 v[76:77], v31 offset0:214 offset1:222
	ds_read2_b32 v[78:79], v31 offset0:247 offset1:255
	s_waitcnt lgkmcnt(8)
	v_cvt_pk_bf16_f32 v80, v48, v50
	v_cvt_pk_bf16_f32 v81, v52, v54
	v_cvt_pk_bf16_f32 v82, v56, v58
	v_cvt_pk_bf16_f32 v83, v60, v62
	v_cvt_pk_bf16_f32 v84, v49, v51
	v_cvt_pk_bf16_f32 v85, v53, v55
	v_cvt_pk_bf16_f32 v86, v57, v59
	v_cvt_pk_bf16_f32 v87, v61, v63
	s_waitcnt lgkmcnt(0)
	v_cvt_pk_bf16_f32 v88, v64, v66
	v_cvt_pk_bf16_f32 v89, v68, v70
	v_cvt_pk_bf16_f32 v90, v72, v74
	v_cvt_pk_bf16_f32 v91, v76, v78
	v_cvt_pk_bf16_f32 v92, v65, v67
	v_cvt_pk_bf16_f32 v93, v69, v71
	v_cvt_pk_bf16_f32 v94, v73, v75
	v_cvt_pk_bf16_f32 v95, v77, v79
	global_store_dwordx4 v116, v[80:83], s[82:83] offset:1024
	global_store_dwordx4 v117, v[84:87], s[82:83] offset:1024
	global_store_dwordx4 v118, v[88:91], s[82:83] offset:1024
	global_store_dwordx4 v119, v[92:95], s[82:83] offset:1024
	s_add_u32 s44, s44, 0x200000
	s_addc_u32 s45, s45, 0
	global_load_dwordx4 v[160:163], v100, s[44:45] nt
	global_load_dwordx4 v[164:167], v101, s[44:45] nt
	global_load_dwordx4 v[168:171], v102, s[44:45] nt
	global_load_dwordx4 v[172:175], v103, s[44:45] nt
	global_load_dwordx4 v[176:179], v104, s[44:45] nt
	global_load_dwordx4 v[180:183], v105, s[44:45] nt
	global_load_dwordx4 v[184:187], v106, s[44:45] nt
	global_load_dwordx4 v[188:191], v107, s[44:45] nt
	s_waitcnt vmcnt(8)
	ds_write2_b32 v32, v128, v129 offset1:1
	ds_write2_b32 v32, v130, v131 offset0:2 offset1:3
	ds_write2_b32 v33, v132, v133 offset1:1
	ds_write2_b32 v34, v134, v135 offset1:1
	ds_write2_b32 v35, v136, v137 offset1:1
	ds_write2_b32 v36, v138, v139 offset1:1
	ds_write2_b32 v37, v140, v141 offset1:1
	ds_write2_b32 v38, v142, v143 offset1:1
	ds_write2_b32 v39, v144, v145 offset1:1
	ds_write2_b32 v40, v146, v147 offset1:1
	ds_write2_b32 v41, v148, v149 offset1:1
	ds_write2_b32 v42, v150, v151 offset1:1
	ds_write2_b32 v43, v152, v153 offset1:1
	ds_write2_b32 v44, v154, v155 offset1:1
	ds_write2_b32 v45, v156, v157 offset1:1
	ds_write2_b32 v46, v158, v159 offset1:1
	s_waitcnt lgkmcnt(0)
	ds_read2_b32 v[48:49], v31 offset0:0 offset1:8
	ds_read2_b32 v[50:51], v31 offset0:33 offset1:41
	ds_read2_b32 v[52:53], v31 offset0:66 offset1:74
	ds_read2_b32 v[54:55], v31 offset0:99 offset1:107
	ds_read2_b32 v[56:57], v31 offset0:132 offset1:140
	ds_read2_b32 v[58:59], v31 offset0:165 offset1:173
	ds_read2_b32 v[60:61], v31 offset0:198 offset1:206
	ds_read2_b32 v[62:63], v31 offset0:231 offset1:239
	ds_read2_b32 v[64:65], v31 offset0:16 offset1:24
	ds_read2_b32 v[66:67], v31 offset0:49 offset1:57
	ds_read2_b32 v[68:69], v31 offset0:82 offset1:90
	ds_read2_b32 v[70:71], v31 offset0:115 offset1:123
	ds_read2_b32 v[72:73], v31 offset0:148 offset1:156
	ds_read2_b32 v[74:75], v31 offset0:181 offset1:189
	ds_read2_b32 v[76:77], v31 offset0:214 offset1:222
	ds_read2_b32 v[78:79], v31 offset0:247 offset1:255
	s_waitcnt lgkmcnt(8)
	v_cvt_pk_bf16_f32 v80, v48, v50
	v_cvt_pk_bf16_f32 v81, v52, v54
	v_cvt_pk_bf16_f32 v82, v56, v58
	v_cvt_pk_bf16_f32 v83, v60, v62
	v_cvt_pk_bf16_f32 v84, v49, v51
	v_cvt_pk_bf16_f32 v85, v53, v55
	v_cvt_pk_bf16_f32 v86, v57, v59
	v_cvt_pk_bf16_f32 v87, v61, v63
	s_waitcnt lgkmcnt(0)
; #define GAS __attribute__((address_space(1)))
; #define LAS __attribute__((address_space(3)))
; #define LDS_WAIT() asm volatile("s_waitcnt lgkmcnt(0)" ::: "memory")
; __device__ __forceinline__ unsigned pk2(float lo, float hi) { const f32x2_t v = {lo, hi}; return __builtin_bit_cast(unsigned, __builtin_convertvector(v, bf16x2_t)); }
; __device__ __forceinline__ void p0_transpose_item(const float* W, int ldw, int src_col0, int k0, bf16_t* WT, int ldk, int dst_row0, int dst_k0, LAS float* scr, int lane) {
; #pragma unroll
;     for (int i = 0; i < 8; ++i) { const int kk = 8 * i + (lane >> 3), n4 = 4 * (lane & 7);
;         const f32x4 w = *(const GAS f32x4*)(W + (size_t)(k0 + kk) * ldw + src_col0 + n4); LAS float* d = scr + kk * 33 + n4; d[0] = w[0]; d[1] = w[1]; d[2] = w[2]; d[3] = w[3]; }
;     LDS_WAIT(); asm volatile("" ::: "memory");
;     const int c = lane & 7;
; #pragma unroll
;     for (int j = 0; j < 4; ++j) { const int n = (lane >> 3) + 8 * j; const LAS float* s = scr + (8 * c) * 33 + n;
;         v4u o; o.x = pk2(s[0 * 33], s[1 * 33]); o.y = pk2(s[2 * 33], s[3 * 33]); o.z = pk2(s[4 * 33], s[5 * 33]); o.w = pk2(s[6 * 33], s[7 * 33]);
;         *(GAS v4u*)(WT + (size_t)(dst_row0 + n) * ldk + dst_k0 + k0 + 8 * c) = o; }
;     LDS_WAIT(); asm volatile("" ::: "memory");
; }
; __global__ void __launch_bounds__(NWAVES * 64, 2) fwd(Args args) {
;     ...
;                     if (r < I_O) { const int kb = r / 32, nb = r % 32; p0_transpose_item(wo, 1024, 32 * nb, 64 * kb, WO_T, 1024, 32 * nb, 0, scr, lane); continue; } r -= I_O;
;                     if (r < I_UP) { const int kb = r / 128, nb = r % 128; p0_transpose_item(wup, FF, 32 * nb, 64 * kb, WUP_T, 1024, 32 * nb, 0, scr, lane); continue; } r -= I_UP;
	v_cvt_pk_bf16_f32 v88, v64, v66
	v_cvt_pk_bf16_f32 v89, v68, v70
	v_cvt_pk_bf16_f32 v90, v72, v74
	v_cvt_pk_bf16_f32 v91, v76, v78
	v_cvt_pk_bf16_f32 v92, v65, v67
	v_cvt_pk_bf16_f32 v93, v69, v71
	v_cvt_pk_bf16_f32 v94, v73, v75
	v_cvt_pk_bf16_f32 v95, v77, v79
	global_store_dwordx4 v116, v[80:83], s[84:85]
	global_store_dwordx4 v117, v[84:87], s[84:85]
	global_store_dwordx4 v118, v[88:91], s[84:85]
	global_store_dwordx4 v119, v[92:95], s[84:85]
	global_load_dwordx4 v[128:131], v108, s[46:47] nt
	global_load_dwordx4 v[132:135], v109, s[46:47] nt
	global_load_dwordx4 v[136:139], v110, s[46:47] nt
	global_load_dwordx4 v[140:143], v111, s[46:47] nt
	global_load_dwordx4 v[144:147], v112, s[46:47] nt
	global_load_dwordx4 v[148:151], v113, s[46:47] nt
	global_load_dwordx4 v[152:155], v114, s[46:47] nt
	global_load_dwordx4 v[156:159], v115, s[46:47] nt
	s_waitcnt vmcnt(8)
	ds_write2_b32 v32, v160, v161 offset1:1
	ds_write2_b32 v32, v162, v163 offset0:2 offset1:3
	ds_write2_b32 v33, v164, v165 offset1:1
	ds_write2_b32 v34, v166, v167 offset1:1
	ds_write2_b32 v35, v168, v169 offset1:1
	ds_write2_b32 v36, v170, v171 offset1:1
	ds_write2_b32 v37, v172, v173 offset1:1
	ds_write2_b32 v38, v174, v175 offset1:1
	ds_write2_b32 v39, v176, v177 offset1:1
	ds_write2_b32 v40, v178, v179 offset1:1
	ds_write2_b32 v41, v180, v181 offset1:1
	ds_write2_b32 v42, v182, v183 offset1:1
	ds_write2_b32 v43, v184, v185 offset1:1
	ds_write2_b32 v44, v186, v187 offset1:1
	ds_write2_b32 v45, v188, v189 offset1:1
	ds_write2_b32 v46, v190, v191 offset1:1
	s_waitcnt lgkmcnt(0)
	ds_read2_b32 v[48:49], v31 offset0:0 offset1:8
	ds_read2_b32 v[50:51], v31 offset0:33 offset1:41
	ds_read2_b32 v[52:53], v31 offset0:66 offset1:74
	ds_read2_b32 v[54:55], v31 offset0:99 offset1:107
	ds_read2_b32 v[56:57], v31 offset0:132 offset1:140
	ds_read2_b32 v[58:59], v31 offset0:165 offset1:173
	ds_read2_b32 v[60:61], v31 offset0:198 offset1:206
	ds_read2_b32 v[62:63], v31 offset0:231 offset1:239
	ds_read2_b32 v[64:65], v31 offset0:16 offset1:24
	ds_read2_b32 v[66:67], v31 offset0:49 offset1:57
	ds_read2_b32 v[68:69], v31 offset0:82 offset1:90
	ds_read2_b32 v[70:71], v31 offset0:115 offset1:123
	ds_read2_b32 v[72:73], v31 offset0:148 offset1:156
	ds_read2_b32 v[74:75], v31 offset0:181 offset1:189
	ds_read2_b32 v[76:77], v31 offset0:214 offset1:222
	ds_read2_b32 v[78:79], v31 offset0:247 offset1:255
	s_waitcnt lgkmcnt(8)
	v_cvt_pk_bf16_f32 v80, v48, v50
	v_cvt_pk_bf16_f32 v81, v52, v54
	v_cvt_pk_bf16_f32 v82, v56, v58
	v_cvt_pk_bf16_f32 v83, v60, v62
	v_cvt_pk_bf16_f32 v84, v49, v51
	v_cvt_pk_bf16_f32 v85, v53, v55
	v_cvt_pk_bf16_f32 v86, v57, v59
	v_cvt_pk_bf16_f32 v87, v61, v63
	s_waitcnt lgkmcnt(0)
	v_cvt_pk_bf16_f32 v88, v64, v66
	v_cvt_pk_bf16_f32 v89, v68, v70
	v_cvt_pk_bf16_f32 v90, v72, v74
	v_cvt_pk_bf16_f32 v91, v76, v78
	v_cvt_pk_bf16_f32 v92, v65, v67
	v_cvt_pk_bf16_f32 v93, v69, v71
	v_cvt_pk_bf16_f32 v94, v73, v75
	v_cvt_pk_bf16_f32 v95, v77, v79
	global_store_dwordx4 v116, v[80:83], s[84:85] offset:1024
	global_store_dwordx4 v117, v[84:87], s[84:85] offset:1024
	global_store_dwordx4 v118, v[88:91], s[84:85] offset:1024
	global_store_dwordx4 v119, v[92:95], s[84:85] offset:1024
	s_add_u32 s46, s46, 0x200000
	s_addc_u32 s47, s47, 0
	global_load_dwordx4 v[160:163], v108, s[46:47] nt
	global_load_dwordx4 v[164:167], v109, s[46:47] nt
	global_load_dwordx4 v[168:171], v110, s[46:47] nt
	global_load_dwordx4 v[172:175], v111, s[46:47] nt
	global_load_dwordx4 v[176:179], v112, s[46:47] nt
	global_load_dwordx4 v[180:183], v113, s[46:47] nt
	global_load_dwordx4 v[184:187], v114, s[46:47] nt
	global_load_dwordx4 v[188:191], v115, s[46:47] nt
	s_waitcnt vmcnt(8)
	ds_write2_b32 v32, v128, v129 offset1:1
	ds_write2_b32 v32, v130, v131 offset0:2 offset1:3
	ds_write2_b32 v33, v132, v133 offset1:1
	ds_write2_b32 v34, v134, v135 offset1:1
	ds_write2_b32 v35, v136, v137 offset1:1
	ds_write2_b32 v36, v138, v139 offset1:1
	ds_write2_b32 v37, v140, v141 offset1:1
	ds_write2_b32 v38, v142, v143 offset1:1
	ds_write2_b32 v39, v144, v145 offset1:1
	ds_write2_b32 v40, v146, v147 offset1:1
	ds_write2_b32 v41, v148, v149 offset1:1
	ds_write2_b32 v42, v150, v151 offset1:1
	ds_write2_b32 v43, v152, v153 offset1:1
	ds_write2_b32 v44, v154, v155 offset1:1
	ds_write2_b32 v45, v156, v157 offset1:1
	ds_write2_b32 v46, v158, v159 offset1:1
	s_waitcnt lgkmcnt(0)
	ds_read2_b32 v[48:49], v31 offset0:0 offset1:8
	ds_read2_b32 v[50:51], v31 offset0:33 offset1:41
	ds_read2_b32 v[52:53], v31 offset0:66 offset1:74
	ds_read2_b32 v[54:55], v31 offset0:99 offset1:107
	ds_read2_b32 v[56:57], v31 offset0:132 offset1:140
	ds_read2_b32 v[58:59], v31 offset0:165 offset1:173
	ds_read2_b32 v[60:61], v31 offset0:198 offset1:206
	ds_read2_b32 v[62:63], v31 offset0:231 offset1:239
	ds_read2_b32 v[64:65], v31 offset0:16 offset1:24
	ds_read2_b32 v[66:67], v31 offset0:49 offset1:57
	ds_read2_b32 v[68:69], v31 offset0:82 offset1:90
	ds_read2_b32 v[70:71], v31 offset0:115 offset1:123
	ds_read2_b32 v[72:73], v31 offset0:148 offset1:156
	ds_read2_b32 v[74:75], v31 offset0:181 offset1:189
	ds_read2_b32 v[76:77], v31 offset0:214 offset1:222
	ds_read2_b32 v[78:79], v31 offset0:247 offset1:255
	s_waitcnt lgkmcnt(8)
	v_cvt_pk_bf16_f32 v80, v48, v50
	v_cvt_pk_bf16_f32 v81, v52, v54
	v_cvt_pk_bf16_f32 v82, v56, v58
	v_cvt_pk_bf16_f32 v83, v60, v62
	v_cvt_pk_bf16_f32 v84, v49, v51
	v_cvt_pk_bf16_f32 v85, v53, v55
	v_cvt_pk_bf16_f32 v86, v57, v59
	v_cvt_pk_bf16_f32 v87, v61, v63
	s_waitcnt lgkmcnt(0)
; #define GAS __attribute__((address_space(1)))
; #define LAS __attribute__((address_space(3)))
; #define LDS_WAIT() asm volatile("s_waitcnt lgkmcnt(0)" ::: "memory")
; __device__ __forceinline__ unsigned pk2(float lo, float hi) { const f32x2_t v = {lo, hi}; return __builtin_bit_cast(unsigned, __builtin_convertvector(v, bf16x2_t)); }
; __device__ __forceinline__ void p0_transpose_item(const float* W, int ldw, int src_col0, int k0, bf16_t* WT, int ldk, int dst_row0, int dst_k0, LAS float* scr, int lane) {
; #pragma unroll
;     for (int i = 0; i < 8; ++i) { const int kk = 8 * i + (lane >> 3), n4 = 4 * (lane & 7);
;         const f32x4 w = *(const GAS f32x4*)(W + (size_t)(k0 + kk) * ldw + src_col0 + n4); LAS float* d = scr + kk * 33 + n4; d[0] = w[0]; d[1] = w[1]; d[2] = w[2]; d[3] = w[3]; }
;     LDS_WAIT(); asm volatile("" ::: "memory");
;     const int c = lane & 7;
; #pragma unroll
;     for (int j = 0; j < 4; ++j) { const int n = (lane >> 3) + 8 * j; const LAS float* s = scr + (8 * c) * 33 + n;
;         v4u o; o.x = pk2(s[0 * 33], s[1 * 33]); o.y = pk2(s[2 * 33], s[3 * 33]); o.z = pk2(s[4 * 33], s[5 * 33]); o.w = pk2(s[6 * 33], s[7 * 33]);
;         *(GAS v4u*)(WT + (size_t)(dst_row0 + n) * ldk + dst_k0 + k0 + 8 * c) = o; }
;     LDS_WAIT(); asm volatile("" ::: "memory");
; }
; __global__ void __launch_bounds__(NWAVES * 64, 2) fwd(Args args) {
;     ...
;                     if (r < I_UP) { const int kb = r / 128, nb = r % 128; p0_transpose_item(wup, FF, 32 * nb, 64 * kb, WUP_T, 1024, 32 * nb, 0, scr, lane); continue; } r -= I_UP;
	v_cvt_pk_bf16_f32 v88, v64, v66
	v_cvt_pk_bf16_f32 v89, v68, v70
	v_cvt_pk_bf16_f32 v90, v72, v74
	v_cvt_pk_bf16_f32 v91, v76, v78
	v_cvt_pk_bf16_f32 v92, v65, v67
	v_cvt_pk_bf16_f32 v93, v69, v71
	v_cvt_pk_bf16_f32 v94, v73, v75
	v_cvt_pk_bf16_f32 v95, v77, v79
	global_store_dwordx4 v116, v[80:83], s[86:87]
	global_store_dwordx4 v117, v[84:87], s[86:87]
	global_store_dwordx4 v118, v[88:91], s[86:87]
	global_store_dwordx4 v119, v[92:95], s[86:87]
	s_add_u32 s46, s46, 0x200000
	s_addc_u32 s47, s47, 0
	global_load_dwordx4 v[128:131], v108, s[46:47] nt
	global_load_dwordx4 v[132:135], v109, s[46:47] nt
	global_load_dwordx4 v[136:139], v110, s[46:47] nt
	global_load_dwordx4 v[140:143], v111, s[46:47] nt
	global_load_dwordx4 v[144:147], v112, s[46:47] nt
	global_load_dwordx4 v[148:151], v113, s[46:47] nt
	global_load_dwordx4 v[152:155], v114, s[46:47] nt
	global_load_dwordx4 v[156:159], v115, s[46:47] nt
	s_waitcnt vmcnt(8)
	ds_write2_b32 v32, v160, v161 offset1:1
	ds_write2_b32 v32, v162, v163 offset0:2 offset1:3
	ds_write2_b32 v33, v164, v165 offset1:1
	ds_write2_b32 v34, v166, v167 offset1:1
	ds_write2_b32 v35, v168, v169 offset1:1
	ds_write2_b32 v36, v170, v171 offset1:1
	ds_write2_b32 v37, v172, v173 offset1:1
	ds_write2_b32 v38, v174, v175 offset1:1
	ds_write2_b32 v39, v176, v177 offset1:1
	ds_write2_b32 v40, v178, v179 offset1:1
	ds_write2_b32 v41, v180, v181 offset1:1
	ds_write2_b32 v42, v182, v183 offset1:1
	ds_write2_b32 v43, v184, v185 offset1:1
	ds_write2_b32 v44, v186, v187 offset1:1
	ds_write2_b32 v45, v188, v189 offset1:1
	ds_write2_b32 v46, v190, v191 offset1:1
	s_waitcnt lgkmcnt(0)
	ds_read2_b32 v[48:49], v31 offset0:0 offset1:8
	ds_read2_b32 v[50:51], v31 offset0:33 offset1:41
	ds_read2_b32 v[52:53], v31 offset0:66 offset1:74
	ds_read2_b32 v[54:55], v31 offset0:99 offset1:107
	ds_read2_b32 v[56:57], v31 offset0:132 offset1:140
	ds_read2_b32 v[58:59], v31 offset0:165 offset1:173
	ds_read2_b32 v[60:61], v31 offset0:198 offset1:206
	ds_read2_b32 v[62:63], v31 offset0:231 offset1:239
	ds_read2_b32 v[64:65], v31 offset0:16 offset1:24
	ds_read2_b32 v[66:67], v31 offset0:49 offset1:57
	ds_read2_b32 v[68:69], v31 offset0:82 offset1:90
	ds_read2_b32 v[70:71], v31 offset0:115 offset1:123
	ds_read2_b32 v[72:73], v31 offset0:148 offset1:156
	ds_read2_b32 v[74:75], v31 offset0:181 offset1:189
	ds_read2_b32 v[76:77], v31 offset0:214 offset1:222
	ds_read2_b32 v[78:79], v31 offset0:247 offset1:255
	s_waitcnt lgkmcnt(8)
	v_cvt_pk_bf16_f32 v80, v48, v50
	v_cvt_pk_bf16_f32 v81, v52, v54
	v_cvt_pk_bf16_f32 v82, v56, v58
	v_cvt_pk_bf16_f32 v83, v60, v62
	v_cvt_pk_bf16_f32 v84, v49, v51
	v_cvt_pk_bf16_f32 v85, v53, v55
	v_cvt_pk_bf16_f32 v86, v57, v59
	v_cvt_pk_bf16_f32 v87, v61, v63
	s_waitcnt lgkmcnt(0)
	v_cvt_pk_bf16_f32 v88, v64, v66
	v_cvt_pk_bf16_f32 v89, v68, v70
	v_cvt_pk_bf16_f32 v90, v72, v74
	v_cvt_pk_bf16_f32 v91, v76, v78
	v_cvt_pk_bf16_f32 v92, v65, v67
	v_cvt_pk_bf16_f32 v93, v69, v71
	v_cvt_pk_bf16_f32 v94, v73, v75
	v_cvt_pk_bf16_f32 v95, v77, v79
	global_store_dwordx4 v116, v[80:83], s[86:87] offset:256
	global_store_dwordx4 v117, v[84:87], s[86:87] offset:256
	global_store_dwordx4 v118, v[88:91], s[86:87] offset:256
	global_store_dwordx4 v119, v[92:95], s[86:87] offset:256
	s_add_u32 s46, s46, 0x200000
	s_addc_u32 s47, s47, 0
	global_load_dwordx4 v[160:163], v108, s[46:47] nt
	global_load_dwordx4 v[164:167], v109, s[46:47] nt
	global_load_dwordx4 v[168:171], v110, s[46:47] nt
	global_load_dwordx4 v[172:175], v111, s[46:47] nt
	global_load_dwordx4 v[176:179], v112, s[46:47] nt
	global_load_dwordx4 v[180:183], v113, s[46:47] nt
	global_load_dwordx4 v[184:187], v114, s[46:47] nt
	global_load_dwordx4 v[188:191], v115, s[46:47] nt
	s_waitcnt vmcnt(8)
	ds_write2_b32 v32, v128, v129 offset1:1
	ds_write2_b32 v32, v130, v131 offset0:2 offset1:3
	ds_write2_b32 v33, v132, v133 offset1:1
	ds_write2_b32 v34, v134, v135 offset1:1
	ds_write2_b32 v35, v136, v137 offset1:1
	ds_write2_b32 v36, v138, v139 offset1:1
	ds_write2_b32 v37, v140, v141 offset1:1
	ds_write2_b32 v38, v142, v143 offset1:1
	ds_write2_b32 v39, v144, v145 offset1:1
	ds_write2_b32 v40, v146, v147 offset1:1
	ds_write2_b32 v41, v148, v149 offset1:1
	ds_write2_b32 v42, v150, v151 offset1:1
	ds_write2_b32 v43, v152, v153 offset1:1
	ds_write2_b32 v44, v154, v155 offset1:1
	ds_write2_b32 v45, v156, v157 offset1:1
	ds_write2_b32 v46, v158, v159 offset1:1
	s_waitcnt lgkmcnt(0)
	ds_read2_b32 v[48:49], v31 offset0:0 offset1:8
	ds_read2_b32 v[50:51], v31 offset0:33 offset1:41
	ds_read2_b32 v[52:53], v31 offset0:66 offset1:74
	ds_read2_b32 v[54:55], v31 offset0:99 offset1:107
	ds_read2_b32 v[56:57], v31 offset0:132 offset1:140
	ds_read2_b32 v[58:59], v31 offset0:165 offset1:173
	ds_read2_b32 v[60:61], v31 offset0:198 offset1:206
	ds_read2_b32 v[62:63], v31 offset0:231 offset1:239
	ds_read2_b32 v[64:65], v31 offset0:16 offset1:24
	ds_read2_b32 v[66:67], v31 offset0:49 offset1:57
	ds_read2_b32 v[68:69], v31 offset0:82 offset1:90
	ds_read2_b32 v[70:71], v31 offset0:115 offset1:123
	ds_read2_b32 v[72:73], v31 offset0:148 offset1:156
	ds_read2_b32 v[74:75], v31 offset0:181 offset1:189
	ds_read2_b32 v[76:77], v31 offset0:214 offset1:222
	ds_read2_b32 v[78:79], v31 offset0:247 offset1:255
	s_waitcnt lgkmcnt(8)
	v_cvt_pk_bf16_f32 v80, v48, v50
	v_cvt_pk_bf16_f32 v81, v52, v54
	v_cvt_pk_bf16_f32 v82, v56, v58
	v_cvt_pk_bf16_f32 v83, v60, v62
	v_cvt_pk_bf16_f32 v84, v49, v51
	v_cvt_pk_bf16_f32 v85, v53, v55
	v_cvt_pk_bf16_f32 v86, v57, v59
	v_cvt_pk_bf16_f32 v87, v61, v63
	s_waitcnt lgkmcnt(0)
; #define GAS __attribute__((address_space(1)))
; #define LAS __attribute__((address_space(3)))
; #define LDS_WAIT() asm volatile("s_waitcnt lgkmcnt(0)" ::: "memory")
; __device__ __forceinline__ unsigned pk2(float lo, float hi) { const f32x2_t v = {lo, hi}; return __builtin_bit_cast(unsigned, __builtin_convertvector(v, bf16x2_t)); }
; __device__ __forceinline__ void p0_transpose_item(const float* W, int ldw, int src_col0, int k0, bf16_t* WT, int ldk, int dst_row0, int dst_k0, LAS float* scr, int lane) {
; #pragma unroll
;     for (int i = 0; i < 8; ++i) { const int kk = 8 * i + (lane >> 3), n4 = 4 * (lane & 7);
;         const f32x4 w = *(const GAS f32x4*)(W + (size_t)(k0 + kk) * ldw + src_col0 + n4); LAS float* d = scr + kk * 33 + n4; d[0] = w[0]; d[1] = w[1]; d[2] = w[2]; d[3] = w[3]; }
;     LDS_WAIT(); asm volatile("" ::: "memory");
;     const int c = lane & 7;
; #pragma unroll
;     for (int j = 0; j < 4; ++j) { const int n = (lane >> 3) + 8 * j; const LAS float* s = scr + (8 * c) * 33 + n;
;         v4u o; o.x = pk2(s[0 * 33], s[1 * 33]); o.y = pk2(s[2 * 33], s[3 * 33]); o.z = pk2(s[4 * 33], s[5 * 33]); o.w = pk2(s[6 * 33], s[7 * 33]);
;         *(GAS v4u*)(WT + (size_t)(dst_row0 + n) * ldk + dst_k0 + k0 + 8 * c) = o; }
;     LDS_WAIT(); asm volatile("" ::: "memory");
; }
; __global__ void __launch_bounds__(NWAVES * 64, 2) fwd(Args args) {
;     ...
;                     if (r < I_UP) { const int kb = r / 128, nb = r % 128; p0_transpose_item(wup, FF, 32 * nb, 64 * kb, WUP_T, 1024, 32 * nb, 0, scr, lane); continue; } r -= I_UP;
	v_cvt_pk_bf16_f32 v88, v64, v66
	v_cvt_pk_bf16_f32 v89, v68, v70
	v_cvt_pk_bf16_f32 v90, v72, v74
	v_cvt_pk_bf16_f32 v91, v76, v78
	v_cvt_pk_bf16_f32 v92, v65, v67
	v_cvt_pk_bf16_f32 v93, v69, v71
	v_cvt_pk_bf16_f32 v94, v73, v75
	v_cvt_pk_bf16_f32 v95, v77, v79
	global_store_dwordx4 v116, v[80:83], s[86:87] offset:512
	global_store_dwordx4 v117, v[84:87], s[86:87] offset:512
	global_store_dwordx4 v118, v[88:91], s[86:87] offset:512
	global_store_dwordx4 v119, v[92:95], s[86:87] offset:512
	s_add_u32 s46, s46, 0x200000
	s_addc_u32 s47, s47, 0
	global_load_dwordx4 v[128:131], v108, s[46:47] nt
	global_load_dwordx4 v[132:135], v109, s[46:47] nt
	global_load_dwordx4 v[136:139], v110, s[46:47] nt
	global_load_dwordx4 v[140:143], v111, s[46:47] nt
	global_load_dwordx4 v[144:147], v112, s[46:47] nt
	global_load_dwordx4 v[148:151], v113, s[46:47] nt
	global_load_dwordx4 v[152:155], v114, s[46:47] nt
	global_load_dwordx4 v[156:159], v115, s[46:47] nt
	s_waitcnt vmcnt(8)
	ds_write2_b32 v32, v160, v161 offset1:1
	ds_write2_b32 v32, v162, v163 offset0:2 offset1:3
	ds_write2_b32 v33, v164, v165 offset1:1
	ds_write2_b32 v34, v166, v167 offset1:1
	ds_write2_b32 v35, v168, v169 offset1:1
	ds_write2_b32 v36, v170, v171 offset1:1
	ds_write2_b32 v37, v172, v173 offset1:1
	ds_write2_b32 v38, v174, v175 offset1:1
	ds_write2_b32 v39, v176, v177 offset1:1
	ds_write2_b32 v40, v178, v179 offset1:1
	ds_write2_b32 v41, v180, v181 offset1:1
	ds_write2_b32 v42, v182, v183 offset1:1
	ds_write2_b32 v43, v184, v185 offset1:1
	ds_write2_b32 v44, v186, v187 offset1:1
	ds_write2_b32 v45, v188, v189 offset1:1
	ds_write2_b32 v46, v190, v191 offset1:1
	s_waitcnt lgkmcnt(0)
	ds_read2_b32 v[48:49], v31 offset0:0 offset1:8
	ds_read2_b32 v[50:51], v31 offset0:33 offset1:41
	ds_read2_b32 v[52:53], v31 offset0:66 offset1:74
	ds_read2_b32 v[54:55], v31 offset0:99 offset1:107
	ds_read2_b32 v[56:57], v31 offset0:132 offset1:140
	ds_read2_b32 v[58:59], v31 offset0:165 offset1:173
	ds_read2_b32 v[60:61], v31 offset0:198 offset1:206
	ds_read2_b32 v[62:63], v31 offset0:231 offset1:239
	ds_read2_b32 v[64:65], v31 offset0:16 offset1:24
	ds_read2_b32 v[66:67], v31 offset0:49 offset1:57
	ds_read2_b32 v[68:69], v31 offset0:82 offset1:90
	ds_read2_b32 v[70:71], v31 offset0:115 offset1:123
	ds_read2_b32 v[72:73], v31 offset0:148 offset1:156
	ds_read2_b32 v[74:75], v31 offset0:181 offset1:189
	ds_read2_b32 v[76:77], v31 offset0:214 offset1:222
	ds_read2_b32 v[78:79], v31 offset0:247 offset1:255
	s_waitcnt lgkmcnt(8)
	v_cvt_pk_bf16_f32 v80, v48, v50
	v_cvt_pk_bf16_f32 v81, v52, v54
	v_cvt_pk_bf16_f32 v82, v56, v58
	v_cvt_pk_bf16_f32 v83, v60, v62
	v_cvt_pk_bf16_f32 v84, v49, v51
	v_cvt_pk_bf16_f32 v85, v53, v55
	v_cvt_pk_bf16_f32 v86, v57, v59
	v_cvt_pk_bf16_f32 v87, v61, v63
	s_waitcnt lgkmcnt(0)
	v_cvt_pk_bf16_f32 v88, v64, v66
	v_cvt_pk_bf16_f32 v89, v68, v70
	v_cvt_pk_bf16_f32 v90, v72, v74
	v_cvt_pk_bf16_f32 v91, v76, v78
	v_cvt_pk_bf16_f32 v92, v65, v67
	v_cvt_pk_bf16_f32 v93, v69, v71
	v_cvt_pk_bf16_f32 v94, v73, v75
	v_cvt_pk_bf16_f32 v95, v77, v79
	global_store_dwordx4 v116, v[80:83], s[86:87] offset:768
	global_store_dwordx4 v117, v[84:87], s[86:87] offset:768
	global_store_dwordx4 v118, v[88:91], s[86:87] offset:768
	global_store_dwordx4 v119, v[92:95], s[86:87] offset:768
	s_add_u32 s46, s46, 0x200000
	s_addc_u32 s47, s47, 0
	global_load_dwordx4 v[160:163], v108, s[46:47] nt
	global_load_dwordx4 v[164:167], v109, s[46:47] nt
	global_load_dwordx4 v[168:171], v110, s[46:47] nt
	global_load_dwordx4 v[172:175], v111, s[46:47] nt
	global_load_dwordx4 v[176:179], v112, s[46:47] nt
	global_load_dwordx4 v[180:183], v113, s[46:47] nt
	global_load_dwordx4 v[184:187], v114, s[46:47] nt
	global_load_dwordx4 v[188:191], v115, s[46:47] nt
	s_waitcnt vmcnt(8)
	ds_write2_b32 v32, v128, v129 offset1:1
	ds_write2_b32 v32, v130, v131 offset0:2 offset1:3
	ds_write2_b32 v33, v132, v133 offset1:1
	ds_write2_b32 v34, v134, v135 offset1:1
	ds_write2_b32 v35, v136, v137 offset1:1
	ds_write2_b32 v36, v138, v139 offset1:1
	ds_write2_b32 v37, v140, v141 offset1:1
	ds_write2_b32 v38, v142, v143 offset1:1
	ds_write2_b32 v39, v144, v145 offset1:1
	ds_write2_b32 v40, v146, v147 offset1:1
	ds_write2_b32 v41, v148, v149 offset1:1
	ds_write2_b32 v42, v150, v151 offset1:1
	ds_write2_b32 v43, v152, v153 offset1:1
	ds_write2_b32 v44, v154, v155 offset1:1
	ds_write2_b32 v45, v156, v157 offset1:1
	ds_write2_b32 v46, v158, v159 offset1:1
	s_waitcnt lgkmcnt(0)
	ds_read2_b32 v[48:49], v31 offset0:0 offset1:8
	ds_read2_b32 v[50:51], v31 offset0:33 offset1:41
	ds_read2_b32 v[52:53], v31 offset0:66 offset1:74
	ds_read2_b32 v[54:55], v31 offset0:99 offset1:107
	ds_read2_b32 v[56:57], v31 offset0:132 offset1:140
	ds_read2_b32 v[58:59], v31 offset0:165 offset1:173
	ds_read2_b32 v[60:61], v31 offset0:198 offset1:206
	ds_read2_b32 v[62:63], v31 offset0:231 offset1:239
	ds_read2_b32 v[64:65], v31 offset0:16 offset1:24
	ds_read2_b32 v[66:67], v31 offset0:49 offset1:57
	ds_read2_b32 v[68:69], v31 offset0:82 offset1:90
	ds_read2_b32 v[70:71], v31 offset0:115 offset1:123
	ds_read2_b32 v[72:73], v31 offset0:148 offset1:156
	ds_read2_b32 v[74:75], v31 offset0:181 offset1:189
	ds_read2_b32 v[76:77], v31 offset0:214 offset1:222
	ds_read2_b32 v[78:79], v31 offset0:247 offset1:255
	s_waitcnt lgkmcnt(8)
	v_cvt_pk_bf16_f32 v80, v48, v50
	v_cvt_pk_bf16_f32 v81, v52, v54
	v_cvt_pk_bf16_f32 v82, v56, v58
	v_cvt_pk_bf16_f32 v83, v60, v62
	v_cvt_pk_bf16_f32 v84, v49, v51
	v_cvt_pk_bf16_f32 v85, v53, v55
	v_cvt_pk_bf16_f32 v86, v57, v59
	v_cvt_pk_bf16_f32 v87, v61, v63
	s_waitcnt lgkmcnt(0)
; #define GAS __attribute__((address_space(1)))
; #define LAS __attribute__((address_space(3)))
; #define LDS_WAIT() asm volatile("s_waitcnt lgkmcnt(0)" ::: "memory")
; __device__ __forceinline__ unsigned pk2(float lo, float hi) { const f32x2_t v = {lo, hi}; return __builtin_bit_cast(unsigned, __builtin_convertvector(v, bf16x2_t)); }
; __device__ __forceinline__ void p0_transpose_item(const float* W, int ldw, int src_col0, int k0, bf16_t* WT, int ldk, int dst_row0, int dst_k0, LAS float* scr, int lane) {
; #pragma unroll
;     for (int i = 0; i < 8; ++i) { const int kk = 8 * i + (lane >> 3), n4 = 4 * (lane & 7);
;         const f32x4 w = *(const GAS f32x4*)(W + (size_t)(k0 + kk) * ldw + src_col0 + n4); LAS float* d = scr + kk * 33 + n4; d[0] = w[0]; d[1] = w[1]; d[2] = w[2]; d[3] = w[3]; }
;     LDS_WAIT(); asm volatile("" ::: "memory");
;     const int c = lane & 7;
; #pragma unroll
;     for (int j = 0; j < 4; ++j) { const int n = (lane >> 3) + 8 * j; const LAS float* s = scr + (8 * c) * 33 + n;
;         v4u o; o.x = pk2(s[0 * 33], s[1 * 33]); o.y = pk2(s[2 * 33], s[3 * 33]); o.z = pk2(s[4 * 33], s[5 * 33]); o.w = pk2(s[6 * 33], s[7 * 33]);
;         *(GAS v4u*)(WT + (size_t)(dst_row0 + n) * ldk + dst_k0 + k0 + 8 * c) = o; }
;     LDS_WAIT(); asm volatile("" ::: "memory");
; }
; __global__ void __launch_bounds__(NWAVES * 64, 2) fwd(Args args) {
;     ...
;                     if (r < I_UP) { const int kb = r / 128, nb = r % 128; p0_transpose_item(wup, FF, 32 * nb, 64 * kb, WUP_T, 1024, 32 * nb, 0, scr, lane); continue; } r -= I_UP;
;                     { const int kb = r / 32, nb = r % 32; p0_transpose_item(wdn, 1024, 32 * nb, 64 * kb, WDN_T, FF, 32 * nb, 0, scr, lane); }
	v_cvt_pk_bf16_f32 v88, v64, v66
	v_cvt_pk_bf16_f32 v89, v68, v70
	v_cvt_pk_bf16_f32 v90, v72, v74
	v_cvt_pk_bf16_f32 v91, v76, v78
	v_cvt_pk_bf16_f32 v92, v65, v67
	v_cvt_pk_bf16_f32 v93, v69, v71
	v_cvt_pk_bf16_f32 v94, v73, v75
	v_cvt_pk_bf16_f32 v95, v77, v79
	global_store_dwordx4 v116, v[80:83], s[86:87] offset:1024
	global_store_dwordx4 v117, v[84:87], s[86:87] offset:1024
	global_store_dwordx4 v118, v[88:91], s[86:87] offset:1024
	global_store_dwordx4 v119, v[92:95], s[86:87] offset:1024
	s_add_u32 s46, s46, 0x200000
	s_addc_u32 s47, s47, 0
	global_load_dwordx4 v[128:131], v108, s[46:47] nt
	global_load_dwordx4 v[132:135], v109, s[46:47] nt
	global_load_dwordx4 v[136:139], v110, s[46:47] nt
	global_load_dwordx4 v[140:143], v111, s[46:47] nt
	global_load_dwordx4 v[144:147], v112, s[46:47] nt
	global_load_dwordx4 v[148:151], v113, s[46:47] nt
	global_load_dwordx4 v[152:155], v114, s[46:47] nt
	global_load_dwordx4 v[156:159], v115, s[46:47] nt
	s_waitcnt vmcnt(8)
	ds_write2_b32 v32, v160, v161 offset1:1
	ds_write2_b32 v32, v162, v163 offset0:2 offset1:3
	ds_write2_b32 v33, v164, v165 offset1:1
	ds_write2_b32 v34, v166, v167 offset1:1
	ds_write2_b32 v35, v168, v169 offset1:1
	ds_write2_b32 v36, v170, v171 offset1:1
	ds_write2_b32 v37, v172, v173 offset1:1
	ds_write2_b32 v38, v174, v175 offset1:1
	ds_write2_b32 v39, v176, v177 offset1:1
	ds_write2_b32 v40, v178, v179 offset1:1
	ds_write2_b32 v41, v180, v181 offset1:1
	ds_write2_b32 v42, v182, v183 offset1:1
	ds_write2_b32 v43, v184, v185 offset1:1
	ds_write2_b32 v44, v186, v187 offset1:1
	ds_write2_b32 v45, v188, v189 offset1:1
	ds_write2_b32 v46, v190, v191 offset1:1
	s_waitcnt lgkmcnt(0)
	ds_read2_b32 v[48:49], v31 offset0:0 offset1:8
	ds_read2_b32 v[50:51], v31 offset0:33 offset1:41
	ds_read2_b32 v[52:53], v31 offset0:66 offset1:74
	ds_read2_b32 v[54:55], v31 offset0:99 offset1:107
	ds_read2_b32 v[56:57], v31 offset0:132 offset1:140
	ds_read2_b32 v[58:59], v31 offset0:165 offset1:173
	ds_read2_b32 v[60:61], v31 offset0:198 offset1:206
	ds_read2_b32 v[62:63], v31 offset0:231 offset1:239
	ds_read2_b32 v[64:65], v31 offset0:16 offset1:24
	ds_read2_b32 v[66:67], v31 offset0:49 offset1:57
	ds_read2_b32 v[68:69], v31 offset0:82 offset1:90
	ds_read2_b32 v[70:71], v31 offset0:115 offset1:123
	ds_read2_b32 v[72:73], v31 offset0:148 offset1:156
	ds_read2_b32 v[74:75], v31 offset0:181 offset1:189
	ds_read2_b32 v[76:77], v31 offset0:214 offset1:222
	ds_read2_b32 v[78:79], v31 offset0:247 offset1:255
	s_waitcnt lgkmcnt(8)
	v_cvt_pk_bf16_f32 v80, v48, v50
	v_cvt_pk_bf16_f32 v81, v52, v54
	v_cvt_pk_bf16_f32 v82, v56, v58
	v_cvt_pk_bf16_f32 v83, v60, v62
	v_cvt_pk_bf16_f32 v84, v49, v51
	v_cvt_pk_bf16_f32 v85, v53, v55
	v_cvt_pk_bf16_f32 v86, v57, v59
	v_cvt_pk_bf16_f32 v87, v61, v63
	s_waitcnt lgkmcnt(0)
	v_cvt_pk_bf16_f32 v88, v64, v66
	v_cvt_pk_bf16_f32 v89, v68, v70
	v_cvt_pk_bf16_f32 v90, v72, v74
	v_cvt_pk_bf16_f32 v91, v76, v78
	v_cvt_pk_bf16_f32 v92, v65, v67
	v_cvt_pk_bf16_f32 v93, v69, v71
	v_cvt_pk_bf16_f32 v94, v73, v75
	v_cvt_pk_bf16_f32 v95, v77, v79
	global_store_dwordx4 v116, v[80:83], s[86:87] offset:1280
	global_store_dwordx4 v117, v[84:87], s[86:87] offset:1280
	global_store_dwordx4 v118, v[88:91], s[86:87] offset:1280
	global_store_dwordx4 v119, v[92:95], s[86:87] offset:1280
	s_add_u32 s46, s46, 0x200000
	s_addc_u32 s47, s47, 0
	global_load_dwordx4 v[160:163], v108, s[46:47] nt
	global_load_dwordx4 v[164:167], v109, s[46:47] nt
	global_load_dwordx4 v[168:171], v110, s[46:47] nt
	global_load_dwordx4 v[172:175], v111, s[46:47] nt
	global_load_dwordx4 v[176:179], v112, s[46:47] nt
	global_load_dwordx4 v[180:183], v113, s[46:47] nt
	global_load_dwordx4 v[184:187], v114, s[46:47] nt
	global_load_dwordx4 v[188:191], v115, s[46:47] nt
	s_waitcnt vmcnt(8)
	ds_write2_b32 v32, v128, v129 offset1:1
	ds_write2_b32 v32, v130, v131 offset0:2 offset1:3
	ds_write2_b32 v33, v132, v133 offset1:1
	ds_write2_b32 v34, v134, v135 offset1:1
	ds_write2_b32 v35, v136, v137 offset1:1
	ds_write2_b32 v36, v138, v139 offset1:1
	ds_write2_b32 v37, v140, v141 offset1:1
	ds_write2_b32 v38, v142, v143 offset1:1
	ds_write2_b32 v39, v144, v145 offset1:1
	ds_write2_b32 v40, v146, v147 offset1:1
	ds_write2_b32 v41, v148, v149 offset1:1
	ds_write2_b32 v42, v150, v151 offset1:1
	ds_write2_b32 v43, v152, v153 offset1:1
	ds_write2_b32 v44, v154, v155 offset1:1
	ds_write2_b32 v45, v156, v157 offset1:1
	ds_write2_b32 v46, v158, v159 offset1:1
	s_waitcnt lgkmcnt(0)
	ds_read2_b32 v[48:49], v31 offset0:0 offset1:8
	ds_read2_b32 v[50:51], v31 offset0:33 offset1:41
	ds_read2_b32 v[52:53], v31 offset0:66 offset1:74
	ds_read2_b32 v[54:55], v31 offset0:99 offset1:107
	ds_read2_b32 v[56:57], v31 offset0:132 offset1:140
	ds_read2_b32 v[58:59], v31 offset0:165 offset1:173
	ds_read2_b32 v[60:61], v31 offset0:198 offset1:206
	ds_read2_b32 v[62:63], v31 offset0:231 offset1:239
	ds_read2_b32 v[64:65], v31 offset0:16 offset1:24
	ds_read2_b32 v[66:67], v31 offset0:49 offset1:57
	ds_read2_b32 v[68:69], v31 offset0:82 offset1:90
	ds_read2_b32 v[70:71], v31 offset0:115 offset1:123
	ds_read2_b32 v[72:73], v31 offset0:148 offset1:156
	ds_read2_b32 v[74:75], v31 offset0:181 offset1:189
	ds_read2_b32 v[76:77], v31 offset0:214 offset1:222
	ds_read2_b32 v[78:79], v31 offset0:247 offset1:255
	s_waitcnt lgkmcnt(8)
	v_cvt_pk_bf16_f32 v80, v48, v50
	v_cvt_pk_bf16_f32 v81, v52, v54
	v_cvt_pk_bf16_f32 v82, v56, v58
	v_cvt_pk_bf16_f32 v83, v60, v62
	v_cvt_pk_bf16_f32 v84, v49, v51
	v_cvt_pk_bf16_f32 v85, v53, v55
	v_cvt_pk_bf16_f32 v86, v57, v59
	v_cvt_pk_bf16_f32 v87, v61, v63
	s_waitcnt lgkmcnt(0)
; #define GAS __attribute__((address_space(1)))
; #define LAS __attribute__((address_space(3)))
; #define LDS_WAIT() asm volatile("s_waitcnt lgkmcnt(0)" ::: "memory")
; __device__ __forceinline__ unsigned pk2(float lo, float hi) { const f32x2_t v = {lo, hi}; return __builtin_bit_cast(unsigned, __builtin_convertvector(v, bf16x2_t)); }
; __device__ __forceinline__ void p0_transpose_item(const float* W, int ldw, int src_col0, int k0, bf16_t* WT, int ldk, int dst_row0, int dst_k0, LAS float* scr, int lane) {
; #pragma unroll
;     for (int i = 0; i < 8; ++i) { const int kk = 8 * i + (lane >> 3), n4 = 4 * (lane & 7);
;         const f32x4 w = *(const GAS f32x4*)(W + (size_t)(k0 + kk) * ldw + src_col0 + n4); LAS float* d = scr + kk * 33 + n4; d[0] = w[0]; d[1] = w[1]; d[2] = w[2]; d[3] = w[3]; }
;     LDS_WAIT(); asm volatile("" ::: "memory");
;     const int c = lane & 7;
; #pragma unroll
;     for (int j = 0; j < 4; ++j) { const int n = (lane >> 3) + 8 * j; const LAS float* s = scr + (8 * c) * 33 + n;
;         v4u o; o.x = pk2(s[0 * 33], s[1 * 33]); o.y = pk2(s[2 * 33], s[3 * 33]); o.z = pk2(s[4 * 33], s[5 * 33]); o.w = pk2(s[6 * 33], s[7 * 33]);
;         *(GAS v4u*)(WT + (size_t)(dst_row0 + n) * ldk + dst_k0 + k0 + 8 * c) = o; }
;     LDS_WAIT(); asm volatile("" ::: "memory");
; }
; __global__ void __launch_bounds__(NWAVES * 64, 2) fwd(Args args) {
;     ...
;                     if (r < I_UP) { const int kb = r / 128, nb = r % 128; p0_transpose_item(wup, FF, 32 * nb, 64 * kb, WUP_T, 1024, 32 * nb, 0, scr, lane); continue; } r -= I_UP;
;                     { const int kb = r / 32, nb = r % 32; p0_transpose_item(wdn, 1024, 32 * nb, 64 * kb, WDN_T, FF, 32 * nb, 0, scr, lane); }
	v_cvt_pk_bf16_f32 v88, v64, v66
	v_cvt_pk_bf16_f32 v89, v68, v70
	v_cvt_pk_bf16_f32 v90, v72, v74
	v_cvt_pk_bf16_f32 v91, v76, v78
	v_cvt_pk_bf16_f32 v92, v65, v67
	v_cvt_pk_bf16_f32 v93, v69, v71
	v_cvt_pk_bf16_f32 v94, v73, v75
	v_cvt_pk_bf16_f32 v95, v77, v79
	global_store_dwordx4 v116, v[80:83], s[86:87] offset:1536
	global_store_dwordx4 v117, v[84:87], s[86:87] offset:1536
	global_store_dwordx4 v118, v[88:91], s[86:87] offset:1536
	global_store_dwordx4 v119, v[92:95], s[86:87] offset:1536
	global_load_dwordx4 v[128:131], v100, s[50:51] nt
	global_load_dwordx4 v[132:135], v101, s[50:51] nt
	global_load_dwordx4 v[136:139], v102, s[50:51] nt
	global_load_dwordx4 v[140:143], v103, s[50:51] nt
	global_load_dwordx4 v[144:147], v104, s[50:51] nt
	global_load_dwordx4 v[148:151], v105, s[50:51] nt
	global_load_dwordx4 v[152:155], v106, s[50:51] nt
	global_load_dwordx4 v[156:159], v107, s[50:51] nt
	s_waitcnt vmcnt(8)
	ds_write2_b32 v32, v160, v161 offset1:1
	ds_write2_b32 v32, v162, v163 offset0:2 offset1:3
	ds_write2_b32 v33, v164, v165 offset1:1
	ds_write2_b32 v34, v166, v167 offset1:1
	ds_write2_b32 v35, v168, v169 offset1:1
	ds_write2_b32 v36, v170, v171 offset1:1
	ds_write2_b32 v37, v172, v173 offset1:1
	ds_write2_b32 v38, v174, v175 offset1:1
	ds_write2_b32 v39, v176, v177 offset1:1
	ds_write2_b32 v40, v178, v179 offset1:1
	ds_write2_b32 v41, v180, v181 offset1:1
	ds_write2_b32 v42, v182, v183 offset1:1
	ds_write2_b32 v43, v184, v185 offset1:1
	ds_write2_b32 v44, v186, v187 offset1:1
	ds_write2_b32 v45, v188, v189 offset1:1
	ds_write2_b32 v46, v190, v191 offset1:1
	s_waitcnt lgkmcnt(0)
	ds_read2_b32 v[48:49], v31 offset0:0 offset1:8
	ds_read2_b32 v[50:51], v31 offset0:33 offset1:41
	ds_read2_b32 v[52:53], v31 offset0:66 offset1:74
	ds_read2_b32 v[54:55], v31 offset0:99 offset1:107
	ds_read2_b32 v[56:57], v31 offset0:132 offset1:140
	ds_read2_b32 v[58:59], v31 offset0:165 offset1:173
	ds_read2_b32 v[60:61], v31 offset0:198 offset1:206
	ds_read2_b32 v[62:63], v31 offset0:231 offset1:239
	ds_read2_b32 v[64:65], v31 offset0:16 offset1:24
	ds_read2_b32 v[66:67], v31 offset0:49 offset1:57
	ds_read2_b32 v[68:69], v31 offset0:82 offset1:90
	ds_read2_b32 v[70:71], v31 offset0:115 offset1:123
	ds_read2_b32 v[72:73], v31 offset0:148 offset1:156
	ds_read2_b32 v[74:75], v31 offset0:181 offset1:189
	ds_read2_b32 v[76:77], v31 offset0:214 offset1:222
	ds_read2_b32 v[78:79], v31 offset0:247 offset1:255
	s_waitcnt lgkmcnt(8)
	v_cvt_pk_bf16_f32 v80, v48, v50
	v_cvt_pk_bf16_f32 v81, v52, v54
	v_cvt_pk_bf16_f32 v82, v56, v58
	v_cvt_pk_bf16_f32 v83, v60, v62
	v_cvt_pk_bf16_f32 v84, v49, v51
	v_cvt_pk_bf16_f32 v85, v53, v55
	v_cvt_pk_bf16_f32 v86, v57, v59
	v_cvt_pk_bf16_f32 v87, v61, v63
	s_waitcnt lgkmcnt(0)
	v_cvt_pk_bf16_f32 v88, v64, v66
	v_cvt_pk_bf16_f32 v89, v68, v70
	v_cvt_pk_bf16_f32 v90, v72, v74
	v_cvt_pk_bf16_f32 v91, v76, v78
	v_cvt_pk_bf16_f32 v92, v65, v67
	v_cvt_pk_bf16_f32 v93, v69, v71
	v_cvt_pk_bf16_f32 v94, v73, v75
	v_cvt_pk_bf16_f32 v95, v77, v79
	global_store_dwordx4 v116, v[80:83], s[86:87] offset:1792
	global_store_dwordx4 v117, v[84:87], s[86:87] offset:1792
	global_store_dwordx4 v118, v[88:91], s[86:87] offset:1792
	global_store_dwordx4 v119, v[92:95], s[86:87] offset:1792
	s_add_u32 s50, s50, 0x200000
	s_addc_u32 s51, s51, 0
	global_load_dwordx4 v[160:163], v100, s[50:51] nt
	global_load_dwordx4 v[164:167], v101, s[50:51] nt
	global_load_dwordx4 v[168:171], v102, s[50:51] nt
	global_load_dwordx4 v[172:175], v103, s[50:51] nt
	global_load_dwordx4 v[176:179], v104, s[50:51] nt
	global_load_dwordx4 v[180:183], v105, s[50:51] nt
	global_load_dwordx4 v[184:187], v106, s[50:51] nt
	global_load_dwordx4 v[188:191], v107, s[50:51] nt
	s_waitcnt vmcnt(8)
	ds_write2_b32 v32, v128, v129 offset1:1
	ds_write2_b32 v32, v130, v131 offset0:2 offset1:3
	ds_write2_b32 v33, v132, v133 offset1:1
	ds_write2_b32 v34, v134, v135 offset1:1
	ds_write2_b32 v35, v136, v137 offset1:1
	ds_write2_b32 v36, v138, v139 offset1:1
	ds_write2_b32 v37, v140, v141 offset1:1
	ds_write2_b32 v38, v142, v143 offset1:1
	ds_write2_b32 v39, v144, v145 offset1:1
	ds_write2_b32 v40, v146, v147 offset1:1
	ds_write2_b32 v41, v148, v149 offset1:1
	ds_write2_b32 v42, v150, v151 offset1:1
	ds_write2_b32 v43, v152, v153 offset1:1
	ds_write2_b32 v44, v154, v155 offset1:1
	ds_write2_b32 v45, v156, v157 offset1:1
	ds_write2_b32 v46, v158, v159 offset1:1
	s_waitcnt lgkmcnt(0)
	ds_read2_b32 v[48:49], v31 offset0:0 offset1:8
	ds_read2_b32 v[50:51], v31 offset0:33 offset1:41
	ds_read2_b32 v[52:53], v31 offset0:66 offset1:74
	ds_read2_b32 v[54:55], v31 offset0:99 offset1:107
	ds_read2_b32 v[56:57], v31 offset0:132 offset1:140
	ds_read2_b32 v[58:59], v31 offset0:165 offset1:173
	ds_read2_b32 v[60:61], v31 offset0:198 offset1:206
	ds_read2_b32 v[62:63], v31 offset0:231 offset1:239
	ds_read2_b32 v[64:65], v31 offset0:16 offset1:24
	ds_read2_b32 v[66:67], v31 offset0:49 offset1:57
	ds_read2_b32 v[68:69], v31 offset0:82 offset1:90
	ds_read2_b32 v[70:71], v31 offset0:115 offset1:123
	ds_read2_b32 v[72:73], v31 offset0:148 offset1:156
	ds_read2_b32 v[74:75], v31 offset0:181 offset1:189
	ds_read2_b32 v[76:77], v31 offset0:214 offset1:222
	ds_read2_b32 v[78:79], v31 offset0:247 offset1:255
	s_waitcnt lgkmcnt(8)
	v_cvt_pk_bf16_f32 v80, v48, v50
	v_cvt_pk_bf16_f32 v81, v52, v54
	v_cvt_pk_bf16_f32 v82, v56, v58
	v_cvt_pk_bf16_f32 v83, v60, v62
	v_cvt_pk_bf16_f32 v84, v49, v51
	v_cvt_pk_bf16_f32 v85, v53, v55
	v_cvt_pk_bf16_f32 v86, v57, v59
	v_cvt_pk_bf16_f32 v87, v61, v63
	s_waitcnt lgkmcnt(0)
; #define GAS __attribute__((address_space(1)))
; #define LAS __attribute__((address_space(3)))
; #define LDS_WAIT() asm volatile("s_waitcnt lgkmcnt(0)" ::: "memory")
; __device__ __forceinline__ unsigned pk2(float lo, float hi) { const f32x2_t v = {lo, hi}; return __builtin_bit_cast(unsigned, __builtin_convertvector(v, bf16x2_t)); }
; __device__ __forceinline__ void p0_transpose_item(const float* W, int ldw, int src_col0, int k0, bf16_t* WT, int ldk, int dst_row0, int dst_k0, LAS float* scr, int lane) {
; #pragma unroll
;     for (int i = 0; i < 8; ++i) { const int kk = 8 * i + (lane >> 3), n4 = 4 * (lane & 7);
;         const f32x4 w = *(const GAS f32x4*)(W + (size_t)(k0 + kk) * ldw + src_col0 + n4); LAS float* d = scr + kk * 33 + n4; d[0] = w[0]; d[1] = w[1]; d[2] = w[2]; d[3] = w[3]; }
;     LDS_WAIT(); asm volatile("" ::: "memory");
;     const int c = lane & 7;
; #pragma unroll
;     for (int j = 0; j < 4; ++j) { const int n = (lane >> 3) + 8 * j; const LAS float* s = scr + (8 * c) * 33 + n;
;         v4u o; o.x = pk2(s[0 * 33], s[1 * 33]); o.y = pk2(s[2 * 33], s[3 * 33]); o.z = pk2(s[4 * 33], s[5 * 33]); o.w = pk2(s[6 * 33], s[7 * 33]);
;         *(GAS v4u*)(WT + (size_t)(dst_row0 + n) * ldk + dst_k0 + k0 + 8 * c) = o; }
;     LDS_WAIT(); asm volatile("" ::: "memory");
; }
; __global__ void __launch_bounds__(NWAVES * 64, 2) fwd(Args args) {
;     ...
;                     { const int kb = r / 32, nb = r % 32; p0_transpose_item(wdn, 1024, 32 * nb, 64 * kb, WDN_T, FF, 32 * nb, 0, scr, lane); }
	v_cvt_pk_bf16_f32 v88, v64, v66
	v_cvt_pk_bf16_f32 v89, v68, v70
	v_cvt_pk_bf16_f32 v90, v72, v74
	v_cvt_pk_bf16_f32 v91, v76, v78
	v_cvt_pk_bf16_f32 v92, v65, v67
	v_cvt_pk_bf16_f32 v93, v69, v71
	v_cvt_pk_bf16_f32 v94, v73, v75
	v_cvt_pk_bf16_f32 v95, v77, v79
	global_store_dwordx4 v120, v[80:83], s[88:89]
	global_store_dwordx4 v121, v[84:87], s[88:89]
	global_store_dwordx4 v122, v[88:91], s[88:89]
	global_store_dwordx4 v123, v[92:95], s[88:89]
	s_add_u32 s50, s50, 0x200000
	s_addc_u32 s51, s51, 0
	global_load_dwordx4 v[128:131], v100, s[50:51] nt
	global_load_dwordx4 v[132:135], v101, s[50:51] nt
	global_load_dwordx4 v[136:139], v102, s[50:51] nt
	global_load_dwordx4 v[140:143], v103, s[50:51] nt
	global_load_dwordx4 v[144:147], v104, s[50:51] nt
	global_load_dwordx4 v[148:151], v105, s[50:51] nt
	global_load_dwordx4 v[152:155], v106, s[50:51] nt
	global_load_dwordx4 v[156:159], v107, s[50:51] nt
	s_waitcnt vmcnt(8)
	ds_write2_b32 v32, v160, v161 offset1:1
	ds_write2_b32 v32, v162, v163 offset0:2 offset1:3
	ds_write2_b32 v33, v164, v165 offset1:1
	ds_write2_b32 v34, v166, v167 offset1:1
	ds_write2_b32 v35, v168, v169 offset1:1
	ds_write2_b32 v36, v170, v171 offset1:1
	ds_write2_b32 v37, v172, v173 offset1:1
	ds_write2_b32 v38, v174, v175 offset1:1
	ds_write2_b32 v39, v176, v177 offset1:1
	ds_write2_b32 v40, v178, v179 offset1:1
	ds_write2_b32 v41, v180, v181 offset1:1
	ds_write2_b32 v42, v182, v183 offset1:1
	ds_write2_b32 v43, v184, v185 offset1:1
	ds_write2_b32 v44, v186, v187 offset1:1
	ds_write2_b32 v45, v188, v189 offset1:1
	ds_write2_b32 v46, v190, v191 offset1:1
	s_waitcnt lgkmcnt(0)
	ds_read2_b32 v[48:49], v31 offset0:0 offset1:8
	ds_read2_b32 v[50:51], v31 offset0:33 offset1:41
	ds_read2_b32 v[52:53], v31 offset0:66 offset1:74
	ds_read2_b32 v[54:55], v31 offset0:99 offset1:107
	ds_read2_b32 v[56:57], v31 offset0:132 offset1:140
	ds_read2_b32 v[58:59], v31 offset0:165 offset1:173
	ds_read2_b32 v[60:61], v31 offset0:198 offset1:206
	ds_read2_b32 v[62:63], v31 offset0:231 offset1:239
	ds_read2_b32 v[64:65], v31 offset0:16 offset1:24
	ds_read2_b32 v[66:67], v31 offset0:49 offset1:57
	ds_read2_b32 v[68:69], v31 offset0:82 offset1:90
	ds_read2_b32 v[70:71], v31 offset0:115 offset1:123
	ds_read2_b32 v[72:73], v31 offset0:148 offset1:156
	ds_read2_b32 v[74:75], v31 offset0:181 offset1:189
	ds_read2_b32 v[76:77], v31 offset0:214 offset1:222
	ds_read2_b32 v[78:79], v31 offset0:247 offset1:255
	s_waitcnt lgkmcnt(8)
	v_cvt_pk_bf16_f32 v80, v48, v50
	v_cvt_pk_bf16_f32 v81, v52, v54
	v_cvt_pk_bf16_f32 v82, v56, v58
	v_cvt_pk_bf16_f32 v83, v60, v62
	v_cvt_pk_bf16_f32 v84, v49, v51
	v_cvt_pk_bf16_f32 v85, v53, v55
	v_cvt_pk_bf16_f32 v86, v57, v59
	v_cvt_pk_bf16_f32 v87, v61, v63
	s_waitcnt lgkmcnt(0)
	v_cvt_pk_bf16_f32 v88, v64, v66
	v_cvt_pk_bf16_f32 v89, v68, v70
	v_cvt_pk_bf16_f32 v90, v72, v74
	v_cvt_pk_bf16_f32 v91, v76, v78
	v_cvt_pk_bf16_f32 v92, v65, v67
	v_cvt_pk_bf16_f32 v93, v69, v71
	v_cvt_pk_bf16_f32 v94, v73, v75
	v_cvt_pk_bf16_f32 v95, v77, v79
	global_store_dwordx4 v120, v[80:83], s[88:89] offset:1024
	global_store_dwordx4 v121, v[84:87], s[88:89] offset:1024
	global_store_dwordx4 v122, v[88:91], s[88:89] offset:1024
	global_store_dwordx4 v123, v[92:95], s[88:89] offset:1024
	s_add_u32 s50, s50, 0x200000
	s_addc_u32 s51, s51, 0
	global_load_dwordx4 v[160:163], v100, s[50:51] nt
	global_load_dwordx4 v[164:167], v101, s[50:51] nt
	global_load_dwordx4 v[168:171], v102, s[50:51] nt
	global_load_dwordx4 v[172:175], v103, s[50:51] nt
	global_load_dwordx4 v[176:179], v104, s[50:51] nt
	global_load_dwordx4 v[180:183], v105, s[50:51] nt
	global_load_dwordx4 v[184:187], v106, s[50:51] nt
	global_load_dwordx4 v[188:191], v107, s[50:51] nt
	s_waitcnt vmcnt(8)
	ds_write2_b32 v32, v128, v129 offset1:1
	ds_write2_b32 v32, v130, v131 offset0:2 offset1:3
	ds_write2_b32 v33, v132, v133 offset1:1
	ds_write2_b32 v34, v134, v135 offset1:1
	ds_write2_b32 v35, v136, v137 offset1:1
	ds_write2_b32 v36, v138, v139 offset1:1
	ds_write2_b32 v37, v140, v141 offset1:1
	ds_write2_b32 v38, v142, v143 offset1:1
	ds_write2_b32 v39, v144, v145 offset1:1
	ds_write2_b32 v40, v146, v147 offset1:1
	ds_write2_b32 v41, v148, v149 offset1:1
	ds_write2_b32 v42, v150, v151 offset1:1
	ds_write2_b32 v43, v152, v153 offset1:1
	ds_write2_b32 v44, v154, v155 offset1:1
	ds_write2_b32 v45, v156, v157 offset1:1
	ds_write2_b32 v46, v158, v159 offset1:1
	s_waitcnt lgkmcnt(0)
	ds_read2_b32 v[48:49], v31 offset0:0 offset1:8
	ds_read2_b32 v[50:51], v31 offset0:33 offset1:41
	ds_read2_b32 v[52:53], v31 offset0:66 offset1:74
	ds_read2_b32 v[54:55], v31 offset0:99 offset1:107
	ds_read2_b32 v[56:57], v31 offset0:132 offset1:140
	ds_read2_b32 v[58:59], v31 offset0:165 offset1:173
	ds_read2_b32 v[60:61], v31 offset0:198 offset1:206
	ds_read2_b32 v[62:63], v31 offset0:231 offset1:239
	ds_read2_b32 v[64:65], v31 offset0:16 offset1:24
	ds_read2_b32 v[66:67], v31 offset0:49 offset1:57
	ds_read2_b32 v[68:69], v31 offset0:82 offset1:90
	ds_read2_b32 v[70:71], v31 offset0:115 offset1:123
	ds_read2_b32 v[72:73], v31 offset0:148 offset1:156
	ds_read2_b32 v[74:75], v31 offset0:181 offset1:189
	ds_read2_b32 v[76:77], v31 offset0:214 offset1:222
	ds_read2_b32 v[78:79], v31 offset0:247 offset1:255
	s_waitcnt lgkmcnt(8)
	v_cvt_pk_bf16_f32 v80, v48, v50
	v_cvt_pk_bf16_f32 v81, v52, v54
	v_cvt_pk_bf16_f32 v82, v56, v58
	v_cvt_pk_bf16_f32 v83, v60, v62
	v_cvt_pk_bf16_f32 v84, v49, v51
	v_cvt_pk_bf16_f32 v85, v53, v55
	v_cvt_pk_bf16_f32 v86, v57, v59
	v_cvt_pk_bf16_f32 v87, v61, v63
	s_waitcnt lgkmcnt(0)
; #define GAS __attribute__((address_space(1)))
; #define LAS __attribute__((address_space(3)))
; #define LDS_WAIT() asm volatile("s_waitcnt lgkmcnt(0)" ::: "memory")
; __device__ __forceinline__ unsigned pk2(float lo, float hi) { const f32x2_t v = {lo, hi}; return __builtin_bit_cast(unsigned, __builtin_convertvector(v, bf16x2_t)); }
; __device__ __forceinline__ void p0_transpose_item(const float* W, int ldw, int src_col0, int k0, bf16_t* WT, int ldk, int dst_row0, int dst_k0, LAS float* scr, int lane) {
; #pragma unroll
;     for (int i = 0; i < 8; ++i) { const int kk = 8 * i + (lane >> 3), n4 = 4 * (lane & 7);
;         const f32x4 w = *(const GAS f32x4*)(W + (size_t)(k0 + kk) * ldw + src_col0 + n4); LAS float* d = scr + kk * 33 + n4; d[0] = w[0]; d[1] = w[1]; d[2] = w[2]; d[3] = w[3]; }
;     LDS_WAIT(); asm volatile("" ::: "memory");
;     const int c = lane & 7;
; #pragma unroll
;     for (int j = 0; j < 4; ++j) { const int n = (lane >> 3) + 8 * j; const LAS float* s = scr + (8 * c) * 33 + n;
;         v4u o; o.x = pk2(s[0 * 33], s[1 * 33]); o.y = pk2(s[2 * 33], s[3 * 33]); o.z = pk2(s[4 * 33], s[5 * 33]); o.w = pk2(s[6 * 33], s[7 * 33]);
;         *(GAS v4u*)(WT + (size_t)(dst_row0 + n) * ldk + dst_k0 + k0 + 8 * c) = o; }
;     LDS_WAIT(); asm volatile("" ::: "memory");
; }
; __global__ void __launch_bounds__(NWAVES * 64, 2) fwd(Args args) {
;     ...
;                     { const int kb = r / 32, nb = r % 32; p0_transpose_item(wdn, 1024, 32 * nb, 64 * kb, WDN_T, FF, 32 * nb, 0, scr, lane); }
	v_cvt_pk_bf16_f32 v88, v64, v66
	v_cvt_pk_bf16_f32 v89, v68, v70
	v_cvt_pk_bf16_f32 v90, v72, v74
	v_cvt_pk_bf16_f32 v91, v76, v78
	v_cvt_pk_bf16_f32 v92, v65, v67
	v_cvt_pk_bf16_f32 v93, v69, v71
	v_cvt_pk_bf16_f32 v94, v73, v75
	v_cvt_pk_bf16_f32 v95, v77, v79
	global_store_dwordx4 v120, v[80:83], s[88:89] offset:2048
	global_store_dwordx4 v121, v[84:87], s[88:89] offset:2048
	global_store_dwordx4 v122, v[88:91], s[88:89] offset:2048
	global_store_dwordx4 v123, v[92:95], s[88:89] offset:2048
	s_add_u32 s50, s50, 0x200000
	s_addc_u32 s51, s51, 0
	global_load_dwordx4 v[128:131], v100, s[50:51] nt
	global_load_dwordx4 v[132:135], v101, s[50:51] nt
	global_load_dwordx4 v[136:139], v102, s[50:51] nt
	global_load_dwordx4 v[140:143], v103, s[50:51] nt
	global_load_dwordx4 v[144:147], v104, s[50:51] nt
	global_load_dwordx4 v[148:151], v105, s[50:51] nt
	global_load_dwordx4 v[152:155], v106, s[50:51] nt
	global_load_dwordx4 v[156:159], v107, s[50:51] nt
	s_waitcnt vmcnt(8)
	ds_write2_b32 v32, v160, v161 offset1:1
	ds_write2_b32 v32, v162, v163 offset0:2 offset1:3
	ds_write2_b32 v33, v164, v165 offset1:1
	ds_write2_b32 v34, v166, v167 offset1:1
	ds_write2_b32 v35, v168, v169 offset1:1
	ds_write2_b32 v36, v170, v171 offset1:1
	ds_write2_b32 v37, v172, v173 offset1:1
	ds_write2_b32 v38, v174, v175 offset1:1
	ds_write2_b32 v39, v176, v177 offset1:1
	ds_write2_b32 v40, v178, v179 offset1:1
	ds_write2_b32 v41, v180, v181 offset1:1
	ds_write2_b32 v42, v182, v183 offset1:1
	ds_write2_b32 v43, v184, v185 offset1:1
	ds_write2_b32 v44, v186, v187 offset1:1
	ds_write2_b32 v45, v188, v189 offset1:1
	ds_write2_b32 v46, v190, v191 offset1:1
	s_waitcnt lgkmcnt(0)
	ds_read2_b32 v[48:49], v31 offset0:0 offset1:8
	ds_read2_b32 v[50:51], v31 offset0:33 offset1:41
	ds_read2_b32 v[52:53], v31 offset0:66 offset1:74
	ds_read2_b32 v[54:55], v31 offset0:99 offset1:107
	ds_read2_b32 v[56:57], v31 offset0:132 offset1:140
	ds_read2_b32 v[58:59], v31 offset0:165 offset1:173
	ds_read2_b32 v[60:61], v31 offset0:198 offset1:206
	ds_read2_b32 v[62:63], v31 offset0:231 offset1:239
	ds_read2_b32 v[64:65], v31 offset0:16 offset1:24
	ds_read2_b32 v[66:67], v31 offset0:49 offset1:57
	ds_read2_b32 v[68:69], v31 offset0:82 offset1:90
	ds_read2_b32 v[70:71], v31 offset0:115 offset1:123
	ds_read2_b32 v[72:73], v31 offset0:148 offset1:156
	ds_read2_b32 v[74:75], v31 offset0:181 offset1:189
	ds_read2_b32 v[76:77], v31 offset0:214 offset1:222
	ds_read2_b32 v[78:79], v31 offset0:247 offset1:255
	s_waitcnt lgkmcnt(8)
	v_cvt_pk_bf16_f32 v80, v48, v50
	v_cvt_pk_bf16_f32 v81, v52, v54
	v_cvt_pk_bf16_f32 v82, v56, v58
	v_cvt_pk_bf16_f32 v83, v60, v62
	v_cvt_pk_bf16_f32 v84, v49, v51
	v_cvt_pk_bf16_f32 v85, v53, v55
	v_cvt_pk_bf16_f32 v86, v57, v59
	v_cvt_pk_bf16_f32 v87, v61, v63
	s_waitcnt lgkmcnt(0)
	v_cvt_pk_bf16_f32 v88, v64, v66
	v_cvt_pk_bf16_f32 v89, v68, v70
	v_cvt_pk_bf16_f32 v90, v72, v74
	v_cvt_pk_bf16_f32 v91, v76, v78
	v_cvt_pk_bf16_f32 v92, v65, v67
	v_cvt_pk_bf16_f32 v93, v69, v71
	v_cvt_pk_bf16_f32 v94, v73, v75
	v_cvt_pk_bf16_f32 v95, v77, v79
	global_store_dwordx4 v120, v[80:83], s[88:89] offset:3072
	global_store_dwordx4 v121, v[84:87], s[88:89] offset:3072
	global_store_dwordx4 v122, v[88:91], s[88:89] offset:3072
	global_store_dwordx4 v123, v[92:95], s[88:89] offset:3072
	s_add_u32 s50, s50, 0x200000
	s_addc_u32 s51, s51, 0
	global_load_dwordx4 v[160:163], v100, s[50:51] nt
	global_load_dwordx4 v[164:167], v101, s[50:51] nt
	global_load_dwordx4 v[168:171], v102, s[50:51] nt
	global_load_dwordx4 v[172:175], v103, s[50:51] nt
	global_load_dwordx4 v[176:179], v104, s[50:51] nt
	global_load_dwordx4 v[180:183], v105, s[50:51] nt
	global_load_dwordx4 v[184:187], v106, s[50:51] nt
	global_load_dwordx4 v[188:191], v107, s[50:51] nt
	s_waitcnt vmcnt(8)
	ds_write2_b32 v32, v128, v129 offset1:1
	ds_write2_b32 v32, v130, v131 offset0:2 offset1:3
	ds_write2_b32 v33, v132, v133 offset1:1
	ds_write2_b32 v34, v134, v135 offset1:1
	ds_write2_b32 v35, v136, v137 offset1:1
	ds_write2_b32 v36, v138, v139 offset1:1
	ds_write2_b32 v37, v140, v141 offset1:1
	ds_write2_b32 v38, v142, v143 offset1:1
	ds_write2_b32 v39, v144, v145 offset1:1
	ds_write2_b32 v40, v146, v147 offset1:1
	ds_write2_b32 v41, v148, v149 offset1:1
	ds_write2_b32 v42, v150, v151 offset1:1
	ds_write2_b32 v43, v152, v153 offset1:1
	ds_write2_b32 v44, v154, v155 offset1:1
	ds_write2_b32 v45, v156, v157 offset1:1
	ds_write2_b32 v46, v158, v159 offset1:1
	s_waitcnt lgkmcnt(0)
	ds_read2_b32 v[48:49], v31 offset0:0 offset1:8
	ds_read2_b32 v[50:51], v31 offset0:33 offset1:41
	ds_read2_b32 v[52:53], v31 offset0:66 offset1:74
	ds_read2_b32 v[54:55], v31 offset0:99 offset1:107
	ds_read2_b32 v[56:57], v31 offset0:132 offset1:140
	ds_read2_b32 v[58:59], v31 offset0:165 offset1:173
	ds_read2_b32 v[60:61], v31 offset0:198 offset1:206
	ds_read2_b32 v[62:63], v31 offset0:231 offset1:239
	ds_read2_b32 v[64:65], v31 offset0:16 offset1:24
	ds_read2_b32 v[66:67], v31 offset0:49 offset1:57
	ds_read2_b32 v[68:69], v31 offset0:82 offset1:90
	ds_read2_b32 v[70:71], v31 offset0:115 offset1:123
	ds_read2_b32 v[72:73], v31 offset0:148 offset1:156
	ds_read2_b32 v[74:75], v31 offset0:181 offset1:189
	ds_read2_b32 v[76:77], v31 offset0:214 offset1:222
	ds_read2_b32 v[78:79], v31 offset0:247 offset1:255
	s_waitcnt lgkmcnt(8)
	v_cvt_pk_bf16_f32 v80, v48, v50
	v_cvt_pk_bf16_f32 v81, v52, v54
	v_cvt_pk_bf16_f32 v82, v56, v58
	v_cvt_pk_bf16_f32 v83, v60, v62
	v_cvt_pk_bf16_f32 v84, v49, v51
	v_cvt_pk_bf16_f32 v85, v53, v55
	v_cvt_pk_bf16_f32 v86, v57, v59
	v_cvt_pk_bf16_f32 v87, v61, v63
	s_waitcnt lgkmcnt(0)
; #define GAS __attribute__((address_space(1)))
; #define LAS __attribute__((address_space(3)))
; #define LDS_WAIT() asm volatile("s_waitcnt lgkmcnt(0)" ::: "memory")
; __device__ __forceinline__ unsigned pk2(float lo, float hi) { const f32x2_t v = {lo, hi}; return __builtin_bit_cast(unsigned, __builtin_convertvector(v, bf16x2_t)); }
; __device__ __forceinline__ void p0_transpose_item(const float* W, int ldw, int src_col0, int k0, bf16_t* WT, int ldk, int dst_row0, int dst_k0, LAS float* scr, int lane) {
; #pragma unroll
;     for (int i = 0; i < 8; ++i) { const int kk = 8 * i + (lane >> 3), n4 = 4 * (lane & 7);
;         const f32x4 w = *(const GAS f32x4*)(W + (size_t)(k0 + kk) * ldw + src_col0 + n4); LAS float* d = scr + kk * 33 + n4; d[0] = w[0]; d[1] = w[1]; d[2] = w[2]; d[3] = w[3]; }
;     LDS_WAIT(); asm volatile("" ::: "memory");
;     const int c = lane & 7;
; #pragma unroll
;     for (int j = 0; j < 4; ++j) { const int n = (lane >> 3) + 8 * j; const LAS float* s = scr + (8 * c) * 33 + n;
;         v4u o; o.x = pk2(s[0 * 33], s[1 * 33]); o.y = pk2(s[2 * 33], s[3 * 33]); o.z = pk2(s[4 * 33], s[5 * 33]); o.w = pk2(s[6 * 33], s[7 * 33]);
;         *(GAS v4u*)(WT + (size_t)(dst_row0 + n) * ldk + dst_k0 + k0 + 8 * c) = o; }
;     LDS_WAIT(); asm volatile("" ::: "memory");
; }
; __global__ void __launch_bounds__(NWAVES * 64, 2) fwd(Args args) {
;     ...
;                     { const int kb = r / 32, nb = r % 32; p0_transpose_item(wdn, 1024, 32 * nb, 64 * kb, WDN_T, FF, 32 * nb, 0, scr, lane); }
	v_cvt_pk_bf16_f32 v88, v64, v66
	v_cvt_pk_bf16_f32 v89, v68, v70
	v_cvt_pk_bf16_f32 v90, v72, v74
	v_cvt_pk_bf16_f32 v91, v76, v78
	v_cvt_pk_bf16_f32 v92, v65, v67
	v_cvt_pk_bf16_f32 v93, v69, v71
	v_cvt_pk_bf16_f32 v94, v73, v75
	v_cvt_pk_bf16_f32 v95, v77, v79
	global_store_dwordx4 v120, v[80:83], s[76:77]
	global_store_dwordx4 v121, v[84:87], s[76:77]
	global_store_dwordx4 v122, v[88:91], s[76:77]
	global_store_dwordx4 v123, v[92:95], s[76:77]
	s_add_u32 s50, s50, 0x200000
	s_addc_u32 s51, s51, 0
	global_load_dwordx4 v[128:131], v100, s[50:51] nt
	global_load_dwordx4 v[132:135], v101, s[50:51] nt
	global_load_dwordx4 v[136:139], v102, s[50:51] nt
	global_load_dwordx4 v[140:143], v103, s[50:51] nt
	global_load_dwordx4 v[144:147], v104, s[50:51] nt
	global_load_dwordx4 v[148:151], v105, s[50:51] nt
	global_load_dwordx4 v[152:155], v106, s[50:51] nt
	global_load_dwordx4 v[156:159], v107, s[50:51] nt
	s_waitcnt vmcnt(8)
	ds_write2_b32 v32, v160, v161 offset1:1
	ds_write2_b32 v32, v162, v163 offset0:2 offset1:3
	ds_write2_b32 v33, v164, v165 offset1:1
	ds_write2_b32 v34, v166, v167 offset1:1
	ds_write2_b32 v35, v168, v169 offset1:1
	ds_write2_b32 v36, v170, v171 offset1:1
	ds_write2_b32 v37, v172, v173 offset1:1
	ds_write2_b32 v38, v174, v175 offset1:1
	ds_write2_b32 v39, v176, v177 offset1:1
	ds_write2_b32 v40, v178, v179 offset1:1
	ds_write2_b32 v41, v180, v181 offset1:1
	ds_write2_b32 v42, v182, v183 offset1:1
	ds_write2_b32 v43, v184, v185 offset1:1
	ds_write2_b32 v44, v186, v187 offset1:1
	ds_write2_b32 v45, v188, v189 offset1:1
	ds_write2_b32 v46, v190, v191 offset1:1
	s_waitcnt lgkmcnt(0)
	ds_read2_b32 v[48:49], v31 offset0:0 offset1:8
	ds_read2_b32 v[50:51], v31 offset0:33 offset1:41
	ds_read2_b32 v[52:53], v31 offset0:66 offset1:74
	ds_read2_b32 v[54:55], v31 offset0:99 offset1:107
	ds_read2_b32 v[56:57], v31 offset0:132 offset1:140
	ds_read2_b32 v[58:59], v31 offset0:165 offset1:173
	ds_read2_b32 v[60:61], v31 offset0:198 offset1:206
	ds_read2_b32 v[62:63], v31 offset0:231 offset1:239
	ds_read2_b32 v[64:65], v31 offset0:16 offset1:24
	ds_read2_b32 v[66:67], v31 offset0:49 offset1:57
	ds_read2_b32 v[68:69], v31 offset0:82 offset1:90
	ds_read2_b32 v[70:71], v31 offset0:115 offset1:123
	ds_read2_b32 v[72:73], v31 offset0:148 offset1:156
	ds_read2_b32 v[74:75], v31 offset0:181 offset1:189
	ds_read2_b32 v[76:77], v31 offset0:214 offset1:222
	ds_read2_b32 v[78:79], v31 offset0:247 offset1:255
	s_waitcnt lgkmcnt(8)
	v_cvt_pk_bf16_f32 v80, v48, v50
	v_cvt_pk_bf16_f32 v81, v52, v54
	v_cvt_pk_bf16_f32 v82, v56, v58
	v_cvt_pk_bf16_f32 v83, v60, v62
	v_cvt_pk_bf16_f32 v84, v49, v51
	v_cvt_pk_bf16_f32 v85, v53, v55
	v_cvt_pk_bf16_f32 v86, v57, v59
	v_cvt_pk_bf16_f32 v87, v61, v63
	s_waitcnt lgkmcnt(0)
	v_cvt_pk_bf16_f32 v88, v64, v66
	v_cvt_pk_bf16_f32 v89, v68, v70
	v_cvt_pk_bf16_f32 v90, v72, v74
	v_cvt_pk_bf16_f32 v91, v76, v78
	v_cvt_pk_bf16_f32 v92, v65, v67
	v_cvt_pk_bf16_f32 v93, v69, v71
	v_cvt_pk_bf16_f32 v94, v73, v75
	v_cvt_pk_bf16_f32 v95, v77, v79
	global_store_dwordx4 v120, v[80:83], s[76:77] offset:1024
	global_store_dwordx4 v121, v[84:87], s[76:77] offset:1024
	global_store_dwordx4 v122, v[88:91], s[76:77] offset:1024
	global_store_dwordx4 v123, v[92:95], s[76:77] offset:1024
	s_add_u32 s50, s50, 0x200000
	s_addc_u32 s51, s51, 0
	global_load_dwordx4 v[160:163], v100, s[50:51] nt
	global_load_dwordx4 v[164:167], v101, s[50:51] nt
	global_load_dwordx4 v[168:171], v102, s[50:51] nt
	global_load_dwordx4 v[172:175], v103, s[50:51] nt
	global_load_dwordx4 v[176:179], v104, s[50:51] nt
	global_load_dwordx4 v[180:183], v105, s[50:51] nt
	global_load_dwordx4 v[184:187], v106, s[50:51] nt
	global_load_dwordx4 v[188:191], v107, s[50:51] nt
	s_waitcnt vmcnt(8)
	ds_write2_b32 v32, v128, v129 offset1:1
	ds_write2_b32 v32, v130, v131 offset0:2 offset1:3
	ds_write2_b32 v33, v132, v133 offset1:1
	ds_write2_b32 v34, v134, v135 offset1:1
	ds_write2_b32 v35, v136, v137 offset1:1
	ds_write2_b32 v36, v138, v139 offset1:1
	ds_write2_b32 v37, v140, v141 offset1:1
	ds_write2_b32 v38, v142, v143 offset1:1
	ds_write2_b32 v39, v144, v145 offset1:1
	ds_write2_b32 v40, v146, v147 offset1:1
	ds_write2_b32 v41, v148, v149 offset1:1
	ds_write2_b32 v42, v150, v151 offset1:1
	ds_write2_b32 v43, v152, v153 offset1:1
	ds_write2_b32 v44, v154, v155 offset1:1
	ds_write2_b32 v45, v156, v157 offset1:1
	ds_write2_b32 v46, v158, v159 offset1:1
	s_waitcnt lgkmcnt(0)
; #define GAS __attribute__((address_space(1)))
; #define LAS __attribute__((address_space(3)))
; #define LDS_WAIT() asm volatile("s_waitcnt lgkmcnt(0)" ::: "memory")
; __device__ __forceinline__ void p0_transpose_item(const float* W, int ldw, int src_col0, int k0, bf16_t* WT, int ldk, int dst_row0, int dst_k0, LAS float* scr, int lane) {
; #pragma unroll
;     for (int i = 0; i < 8; ++i) { const int kk = 8 * i + (lane >> 3), n4 = 4 * (lane & 7);
;         const f32x4 w = *(const GAS f32x4*)(W + (size_t)(k0 + kk) * ldw + src_col0 + n4); LAS float* d = scr + kk * 33 + n4; d[0] = w[0]; d[1] = w[1]; d[2] = w[2]; d[3] = w[3]; }
;     LDS_WAIT(); asm volatile("" ::: "memory");
;     const int c = lane & 7;
; #pragma unroll
;     for (int j = 0; j < 4; ++j) { const int n = (lane >> 3) + 8 * j; const LAS float* s = scr + (8 * c) * 33 + n;
;         v4u o; o.x = pk2(s[0 * 33], s[1 * 33]); o.y = pk2(s[2 * 33], s[3 * 33]); o.z = pk2(s[4 * 33], s[5 * 33]); o.w = pk2(s[6 * 33], s[7 * 33]);
;         *(GAS v4u*)(WT + (size_t)(dst_row0 + n) * ldk + dst_k0 + k0 + 8 * c) = o; }
;     LDS_WAIT(); asm volatile("" ::: "memory");
; }
; __global__ void __launch_bounds__(NWAVES * 64, 2) fwd(Args args) {
;     ...
;                 if (blockIdx.x < 64) for (int it = ((int)blockIdx.x - 32) * NWAVES + wave; it < I_BA + I_BB + I_O + I_UP + I_DN; it += 32 * NWAVES) {
;                     int r = it;
;                     if (r < I_BA) { const int kb = r / 32, nb = r % 32; p0_transpose_item(wba, 1024, 32 * nb, 64 * kb, WBAB_T, 1024, 32 * nb, 0, scr, lane); continue; } r -= I_BA;
;                     if (r < I_BB) { const int kb = r / 32, nb = r % 32; p0_transpose_item(wbb, 1024, 32 * nb, 64 * kb, WBAB_T, 1024, 32 * nb, 512, scr, lane); continue; } r -= I_BB;
;                     if (r < I_O) { const int kb = r / 32, nb = r % 32; p0_transpose_item(wo, 1024, 32 * nb, 64 * kb, WO_T, 1024, 32 * nb, 0, scr, lane); continue; } r -= I_O;
;                     if (r < I_UP) { const int kb = r / 128, nb = r % 128; p0_transpose_item(wup, FF, 32 * nb, 64 * kb, WUP_T, 1024, 32 * nb, 0, scr, lane); continue; } r -= I_UP;
;                     { const int kb = r / 32, nb = r % 32; p0_transpose_item(wdn, 1024, 32 * nb, 64 * kb, WDN_T, FF, 32 * nb, 0, scr, lane); }
	ds_read2_b32 v[48:49], v31 offset0:0 offset1:8
	ds_read2_b32 v[50:51], v31 offset0:33 offset1:41
	ds_read2_b32 v[52:53], v31 offset0:66 offset1:74
	ds_read2_b32 v[54:55], v31 offset0:99 offset1:107
	ds_read2_b32 v[56:57], v31 offset0:132 offset1:140
	ds_read2_b32 v[58:59], v31 offset0:165 offset1:173
	ds_read2_b32 v[60:61], v31 offset0:198 offset1:206
	ds_read2_b32 v[62:63], v31 offset0:231 offset1:239
	ds_read2_b32 v[64:65], v31 offset0:16 offset1:24
	ds_read2_b32 v[66:67], v31 offset0:49 offset1:57
	ds_read2_b32 v[68:69], v31 offset0:82 offset1:90
	ds_read2_b32 v[70:71], v31 offset0:115 offset1:123
	ds_read2_b32 v[72:73], v31 offset0:148 offset1:156
	ds_read2_b32 v[74:75], v31 offset0:181 offset1:189
	ds_read2_b32 v[76:77], v31 offset0:214 offset1:222
	ds_read2_b32 v[78:79], v31 offset0:247 offset1:255
	s_waitcnt lgkmcnt(8)
	v_cvt_pk_bf16_f32 v80, v48, v50
	v_cvt_pk_bf16_f32 v81, v52, v54
	v_cvt_pk_bf16_f32 v82, v56, v58
	v_cvt_pk_bf16_f32 v83, v60, v62
	v_cvt_pk_bf16_f32 v84, v49, v51
	v_cvt_pk_bf16_f32 v85, v53, v55
	v_cvt_pk_bf16_f32 v86, v57, v59
	v_cvt_pk_bf16_f32 v87, v61, v63
	s_waitcnt lgkmcnt(0)
	v_cvt_pk_bf16_f32 v88, v64, v66
	v_cvt_pk_bf16_f32 v89, v68, v70
	v_cvt_pk_bf16_f32 v90, v72, v74
	v_cvt_pk_bf16_f32 v91, v76, v78
	v_cvt_pk_bf16_f32 v92, v65, v67
	v_cvt_pk_bf16_f32 v93, v69, v71
	v_cvt_pk_bf16_f32 v94, v73, v75
	v_cvt_pk_bf16_f32 v95, v77, v79
	global_store_dwordx4 v120, v[80:83], s[76:77] offset:2048
	global_store_dwordx4 v121, v[84:87], s[76:77] offset:2048
	global_store_dwordx4 v122, v[88:91], s[76:77] offset:2048
	global_store_dwordx4 v123, v[92:95], s[76:77] offset:2048
	s_waitcnt vmcnt(0)
	ds_write2_b32 v32, v160, v161 offset1:1
	ds_write2_b32 v32, v162, v163 offset0:2 offset1:3
	ds_write2_b32 v33, v164, v165 offset1:1
	ds_write2_b32 v34, v166, v167 offset1:1
	ds_write2_b32 v35, v168, v169 offset1:1
	ds_write2_b32 v36, v170, v171 offset1:1
	ds_write2_b32 v37, v172, v173 offset1:1
	ds_write2_b32 v38, v174, v175 offset1:1
	ds_write2_b32 v39, v176, v177 offset1:1
	ds_write2_b32 v40, v178, v179 offset1:1
	ds_write2_b32 v41, v180, v181 offset1:1
	ds_write2_b32 v42, v182, v183 offset1:1
	ds_write2_b32 v43, v184, v185 offset1:1
	ds_write2_b32 v44, v186, v187 offset1:1
	ds_write2_b32 v45, v188, v189 offset1:1
	ds_write2_b32 v46, v190, v191 offset1:1
	s_waitcnt lgkmcnt(0)
	ds_read2_b32 v[48:49], v31 offset0:0 offset1:8
	ds_read2_b32 v[50:51], v31 offset0:33 offset1:41
	ds_read2_b32 v[52:53], v31 offset0:66 offset1:74
	ds_read2_b32 v[54:55], v31 offset0:99 offset1:107
	ds_read2_b32 v[56:57], v31 offset0:132 offset1:140
	ds_read2_b32 v[58:59], v31 offset0:165 offset1:173
	ds_read2_b32 v[60:61], v31 offset0:198 offset1:206
	ds_read2_b32 v[62:63], v31 offset0:231 offset1:239
	ds_read2_b32 v[64:65], v31 offset0:16 offset1:24
	ds_read2_b32 v[66:67], v31 offset0:49 offset1:57
	ds_read2_b32 v[68:69], v31 offset0:82 offset1:90
	ds_read2_b32 v[70:71], v31 offset0:115 offset1:123
	ds_read2_b32 v[72:73], v31 offset0:148 offset1:156
	ds_read2_b32 v[74:75], v31 offset0:181 offset1:189
	ds_read2_b32 v[76:77], v31 offset0:214 offset1:222
	ds_read2_b32 v[78:79], v31 offset0:247 offset1:255
	s_waitcnt lgkmcnt(8)
	v_cvt_pk_bf16_f32 v80, v48, v50
	v_cvt_pk_bf16_f32 v81, v52, v54
	v_cvt_pk_bf16_f32 v82, v56, v58
	v_cvt_pk_bf16_f32 v83, v60, v62
	v_cvt_pk_bf16_f32 v84, v49, v51
	v_cvt_pk_bf16_f32 v85, v53, v55
	v_cvt_pk_bf16_f32 v86, v57, v59
	v_cvt_pk_bf16_f32 v87, v61, v63
	s_waitcnt lgkmcnt(0)
	v_cvt_pk_bf16_f32 v88, v64, v66
	v_cvt_pk_bf16_f32 v89, v68, v70
	v_cvt_pk_bf16_f32 v90, v72, v74
	v_cvt_pk_bf16_f32 v91, v76, v78
	v_cvt_pk_bf16_f32 v92, v65, v67
	v_cvt_pk_bf16_f32 v93, v69, v71
	v_cvt_pk_bf16_f32 v94, v73, v75
	v_cvt_pk_bf16_f32 v95, v77, v79
	global_store_dwordx4 v120, v[80:83], s[76:77] offset:3072
	global_store_dwordx4 v121, v[84:87], s[76:77] offset:3072
	global_store_dwordx4 v122, v[88:91], s[76:77] offset:3072
	global_store_dwordx4 v123, v[92:95], s[76:77] offset:3072
